# ctx_combine vector loads prefetched; zt loads issued together; FFT table staging loads issued together (without attention prologue change)
# speedup vs baseline: 1.0249x; 1.0064x over previous
.LBB0_737:
	s_and_b32 s0, s8, 0xffffffc0
	s_addk_i32 s0, 0x4000
	v_or_b32_e32 v20, s0, v2
	v_ashrrev_i32_e32 v21, 31, v20
	v_lshlrev_b64 v[20:21], 12, v[20:21]
	v_lshl_add_u64 v[20:21], s[86:87], 0, v[20:21]
	v_lshl_add_u64 v[20:21], v[20:21], 0, s[68:69]
	v_lshl_add_u64 v[20:21], v[20:21], 0, v[98:99]
	v_add_co_u32_e32 v20, vcc, 0x7100000, v20
	s_and_b32 s1, s9, 0xc0
	s_nop 0
	v_addc_co_u32_e32 v21, vcc, 0, v21, vcc
	global_load_dwordx4 v[100:103], v[20:21], off offset:1536
	s_and_b32 s10, s8, 0xffffff00
	s_or_b32 s10, s10, s1
	v_or_b32_e32 v20, s0, v4
	v_ashrrev_i32_e32 v21, 31, v20
	v_lshlrev_b64 v[20:21], 12, v[20:21]
	v_lshl_add_u64 v[20:21], s[86:87], 0, v[20:21]
	v_lshl_add_u64 v[20:21], v[20:21], 0, s[68:69]
	v_lshl_add_u64 v[20:21], v[20:21], 0, v[98:99]
	v_add_co_u32_e32 v20, vcc, s95, v20
	s_nop 1
	v_addc_co_u32_e32 v21, vcc, 0, v21, vcc
	global_load_dwordx4 v[104:107], v[20:21], off offset:1536
	v_or_b32_e32 v20, s0, v6
	v_ashrrev_i32_e32 v21, 31, v20
	v_lshlrev_b64 v[20:21], 12, v[20:21]
	v_lshl_add_u64 v[20:21], s[86:87], 0, v[20:21]
	v_lshl_add_u64 v[20:21], v[20:21], 0, s[68:69]
	v_lshl_add_u64 v[20:21], v[20:21], 0, v[98:99]
	v_add_co_u32_e32 v20, vcc, s95, v20
	s_nop 1
	v_addc_co_u32_e32 v21, vcc, 0, v21, vcc
	global_load_dwordx4 v[108:111], v[20:21], off offset:1536
	v_or_b32_e32 v20, s0, v8
	v_ashrrev_i32_e32 v21, 31, v20
	v_lshlrev_b64 v[20:21], 12, v[20:21]
	v_lshl_add_u64 v[20:21], s[86:87], 0, v[20:21]
	v_lshl_add_u64 v[20:21], v[20:21], 0, s[68:69]
	v_lshl_add_u64 v[20:21], v[20:21], 0, v[98:99]
	v_add_co_u32_e32 v20, vcc, s95, v20
	s_nop 1
	v_addc_co_u32_e32 v21, vcc, 0, v21, vcc
	global_load_dwordx4 v[112:115], v[20:21], off offset:1536
	v_or_b32_e32 v20, s0, v10
	v_ashrrev_i32_e32 v21, 31, v20
	v_lshlrev_b64 v[20:21], 12, v[20:21]
	v_lshl_add_u64 v[20:21], s[86:87], 0, v[20:21]
	v_lshl_add_u64 v[20:21], v[20:21], 0, s[68:69]
	v_lshl_add_u64 v[20:21], v[20:21], 0, v[98:99]
	v_add_co_u32_e32 v20, vcc, s95, v20
	s_nop 1
	v_addc_co_u32_e32 v21, vcc, 0, v21, vcc
	global_load_dwordx4 v[116:119], v[20:21], off offset:1536
	v_or_b32_e32 v20, s0, v12
	v_ashrrev_i32_e32 v21, 31, v20
	v_lshlrev_b64 v[20:21], 12, v[20:21]
	v_lshl_add_u64 v[20:21], s[86:87], 0, v[20:21]
	v_lshl_add_u64 v[20:21], v[20:21], 0, s[68:69]
	v_lshl_add_u64 v[20:21], v[20:21], 0, v[98:99]
	v_add_co_u32_e32 v20, vcc, s95, v20
	s_nop 1
	v_addc_co_u32_e32 v21, vcc, 0, v21, vcc
	global_load_dwordx4 v[120:123], v[20:21], off offset:1536
	v_or_b32_e32 v20, s0, v14
	v_ashrrev_i32_e32 v21, 31, v20
	v_lshlrev_b64 v[20:21], 12, v[20:21]
	v_lshl_add_u64 v[20:21], s[86:87], 0, v[20:21]
	v_lshl_add_u64 v[20:21], v[20:21], 0, s[68:69]
	v_lshl_add_u64 v[20:21], v[20:21], 0, v[98:99]
	v_add_co_u32_e32 v20, vcc, s95, v20
	s_nop 1
	v_addc_co_u32_e32 v21, vcc, 0, v21, vcc
	global_load_dwordx4 v[124:127], v[20:21], off offset:1536
	v_or_b32_e32 v20, s0, v16
	v_ashrrev_i32_e32 v21, 31, v20
	v_lshlrev_b64 v[20:21], 12, v[20:21]
	v_lshl_add_u64 v[20:21], s[86:87], 0, v[20:21]
	v_lshl_add_u64 v[20:21], v[20:21], 0, s[68:69]
	v_lshl_add_u64 v[20:21], v[20:21], 0, v[98:99]
	v_add_co_u32_e32 v20, vcc, s95, v20
	s_and_b32 s0, s8, 0xc0
	s_nop 0
	v_addc_co_u32_e32 v21, vcc, 0, v21, vcc
	global_load_dwordx4 v[128:131], v[20:21], off offset:1536
	s_lshl_b32 s0, s0, 1
	s_add_u32 s0, s2, s0
	s_addc_u32 s1, s7, 0
	s_add_i32 s22, s22, s80
	s_add_i32 s9, s9, s66
	s_add_i32 s8, s8, s11
	s_cmp_lt_i32 s22, s4
	s_waitcnt vmcnt(0)
	ds_write2_b32 v3, v100, v101 offset1:1
	ds_write2_b32 v3, v102, v103 offset0:2 offset1:3
	ds_write2_b32 v5, v104, v105 offset1:1
	ds_write2_b32 v5, v106, v107 offset0:2 offset1:3
	ds_write2_b32 v7, v108, v109 offset1:1
	ds_write2_b32 v7, v110, v111 offset0:2 offset1:3
	ds_write2_b32 v9, v112, v113 offset1:1
	ds_write2_b32 v9, v114, v115 offset0:2 offset1:3
	ds_write2_b32 v11, v116, v117 offset1:1
	ds_write2_b32 v11, v118, v119 offset0:2 offset1:3
	ds_write2_b32 v13, v120, v121 offset1:1
	ds_write2_b32 v13, v122, v123 offset0:2 offset1:3
	ds_write2_b32 v15, v124, v125 offset1:1
	ds_write2_b32 v15, v126, v127 offset0:2 offset1:3
	ds_write2_b32 v17, v128, v129 offset1:1
	ds_write2_b32 v17, v130, v131 offset0:2 offset1:3
	s_waitcnt lgkmcnt(0)
	ds_read_u16 v19, v18 offset:132
	ds_read_u16 v21, v18 offset:264
	ds_read_u16 v22, v18 offset:396
	ds_read_u16 v23, v18 offset:528
	ds_read_u16 v24, v18 offset:660
	ds_read_u16 v25, v18 offset:792
	ds_read_u16 v26, v18 offset:924
	ds_read_u16 v20, v18
	ds_read_u16 v27, v18 offset:16
	s_waitcnt lgkmcnt(6)
	v_lshl_or_b32 v21, v22, 16, v21
	s_waitcnt lgkmcnt(4)
	v_lshl_or_b32 v22, v24, 16, v23
	v_or_b32_e32 v24, s10, v2
	s_waitcnt lgkmcnt(2)
	v_lshl_or_b32 v23, v26, 16, v25
	v_ashrrev_i32_e32 v25, 31, v24
	v_lshlrev_b64 v[24:25], 10, v[24:25]
	v_lshl_add_u64 v[24:25], s[0:1], 0, v[24:25]
	s_waitcnt lgkmcnt(1)
	v_lshl_or_b32 v20, v19, 16, v20
	v_lshl_add_u64 v[24:25], v[24:25], 0, v[98:99]
	global_store_dwordx4 v[24:25], v[20:23], off
	ds_read_u16 v19, v18 offset:148
	ds_read_u16 v21, v18 offset:280
	ds_read_u16 v22, v18 offset:412
	ds_read_u16 v23, v18 offset:544
	ds_read_u16 v24, v18 offset:676
	ds_read_u16 v25, v18 offset:808
	ds_read_u16 v26, v18 offset:940
	s_waitcnt lgkmcnt(4)
	v_lshl_or_b32 v21, v22, 16, v21
	v_lshl_or_b32 v20, v19, 16, v27
	s_waitcnt lgkmcnt(2)
	v_lshl_or_b32 v22, v24, 16, v23
	v_or_b32_e32 v24, s10, v4
	s_waitcnt lgkmcnt(0)
	v_lshl_or_b32 v23, v26, 16, v25
	v_ashrrev_i32_e32 v25, 31, v24
	v_lshlrev_b64 v[24:25], 10, v[24:25]
	v_lshl_add_u64 v[24:25], s[0:1], 0, v[24:25]
	v_lshl_add_u64 v[24:25], v[24:25], 0, v[98:99]
	global_store_dwordx4 v[24:25], v[20:23], off
	ds_read_u16 v19, v18 offset:164
	ds_read_u16 v21, v18 offset:296
	ds_read_u16 v22, v18 offset:428
	ds_read_u16 v23, v18 offset:560
	ds_read_u16 v24, v18 offset:692
	ds_read_u16 v25, v18 offset:824
	ds_read_u16 v26, v18 offset:956
	ds_read_u16 v20, v18 offset:32
	ds_read_u16 v27, v18 offset:48
	s_waitcnt lgkmcnt(6)
	v_lshl_or_b32 v21, v22, 16, v21
	s_waitcnt lgkmcnt(4)
	v_lshl_or_b32 v22, v24, 16, v23
	v_or_b32_e32 v24, s10, v6
	s_waitcnt lgkmcnt(2)
	v_lshl_or_b32 v23, v26, 16, v25
	v_ashrrev_i32_e32 v25, 31, v24
	v_lshlrev_b64 v[24:25], 10, v[24:25]
	v_lshl_add_u64 v[24:25], s[0:1], 0, v[24:25]
	s_waitcnt lgkmcnt(1)
	v_lshl_or_b32 v20, v19, 16, v20
	v_lshl_add_u64 v[24:25], v[24:25], 0, v[98:99]
	global_store_dwordx4 v[24:25], v[20:23], off
	ds_read_u16 v19, v18 offset:180
	ds_read_u16 v21, v18 offset:312
	ds_read_u16 v22, v18 offset:444
	ds_read_u16 v23, v18 offset:576
	ds_read_u16 v24, v18 offset:708
	ds_read_u16 v25, v18 offset:840
	ds_read_u16 v26, v18 offset:972
	s_waitcnt lgkmcnt(4)
	v_lshl_or_b32 v21, v22, 16, v21
	v_lshl_or_b32 v20, v19, 16, v27
	s_waitcnt lgkmcnt(2)
	v_lshl_or_b32 v22, v24, 16, v23
	v_or_b32_e32 v24, s10, v8
	s_waitcnt lgkmcnt(0)
	v_lshl_or_b32 v23, v26, 16, v25
	v_ashrrev_i32_e32 v25, 31, v24
	v_lshlrev_b64 v[24:25], 10, v[24:25]
	v_lshl_add_u64 v[24:25], s[0:1], 0, v[24:25]
	v_lshl_add_u64 v[24:25], v[24:25], 0, v[98:99]
	global_store_dwordx4 v[24:25], v[20:23], off
	ds_read_u16 v19, v18 offset:64
	ds_read_u16 v20, v18 offset:196
	ds_read_u16 v21, v18 offset:328
	ds_read_u16 v22, v18 offset:460
	ds_read_u16 v23, v18 offset:592
	ds_read_u16 v24, v18 offset:724
	ds_read_u16 v25, v18 offset:856
	ds_read_u16 v26, v18 offset:988
	s_waitcnt lgkmcnt(4)
	v_lshl_or_b32 v21, v22, 16, v21
	v_lshl_or_b32 v20, v20, 16, v19
	s_waitcnt lgkmcnt(2)
	v_lshl_or_b32 v22, v24, 16, v23
	v_or_b32_e32 v24, s10, v10
	s_waitcnt lgkmcnt(0)
	v_lshl_or_b32 v23, v26, 16, v25
	v_ashrrev_i32_e32 v25, 31, v24
	v_lshlrev_b64 v[24:25], 10, v[24:25]
	v_lshl_add_u64 v[24:25], s[0:1], 0, v[24:25]
	v_lshl_add_u64 v[24:25], v[24:25], 0, v[98:99]
	global_store_dwordx4 v[24:25], v[20:23], off
	ds_read_u16 v19, v18 offset:80
	ds_read_u16 v20, v18 offset:212
	ds_read_u16 v21, v18 offset:344
	ds_read_u16 v22, v18 offset:476
	ds_read_u16 v23, v18 offset:608
	ds_read_u16 v24, v18 offset:740
	ds_read_u16 v25, v18 offset:872
	ds_read_u16 v26, v18 offset:1004
	s_waitcnt lgkmcnt(4)
	v_lshl_or_b32 v21, v22, 16, v21
	v_lshl_or_b32 v20, v20, 16, v19
	s_waitcnt lgkmcnt(2)
	v_lshl_or_b32 v22, v24, 16, v23
	v_or_b32_e32 v24, s10, v12
	s_waitcnt lgkmcnt(0)
	v_lshl_or_b32 v23, v26, 16, v25
	v_ashrrev_i32_e32 v25, 31, v24
	v_lshlrev_b64 v[24:25], 10, v[24:25]
	v_lshl_add_u64 v[24:25], s[0:1], 0, v[24:25]
	v_lshl_add_u64 v[24:25], v[24:25], 0, v[98:99]
	global_store_dwordx4 v[24:25], v[20:23], off
	ds_read_u16 v19, v18 offset:96
	ds_read_u16 v20, v18 offset:228
	ds_read_u16 v21, v18 offset:360
	ds_read_u16 v22, v18 offset:492
	ds_read_u16 v23, v18 offset:624
	ds_read_u16 v24, v18 offset:756
	ds_read_u16 v25, v18 offset:888
	ds_read_u16 v26, v18 offset:1020
	s_waitcnt lgkmcnt(4)
	v_lshl_or_b32 v21, v22, 16, v21
	v_lshl_or_b32 v20, v20, 16, v19
	s_waitcnt lgkmcnt(2)
	v_lshl_or_b32 v22, v24, 16, v23
	v_or_b32_e32 v24, s10, v14
	s_waitcnt lgkmcnt(0)
	v_lshl_or_b32 v23, v26, 16, v25
	v_ashrrev_i32_e32 v25, 31, v24
	v_lshlrev_b64 v[24:25], 10, v[24:25]
	v_lshl_add_u64 v[24:25], s[0:1], 0, v[24:25]
	v_lshl_add_u64 v[24:25], v[24:25], 0, v[98:99]
	global_store_dwordx4 v[24:25], v[20:23], off
	ds_read_u16 v19, v18 offset:112
	ds_read_u16 v20, v18 offset:244
	ds_read_u16 v21, v18 offset:376
	ds_read_u16 v22, v18 offset:508
	ds_read_u16 v23, v18 offset:640
	ds_read_u16 v24, v18 offset:772
	ds_read_u16 v25, v18 offset:904
	ds_read_u16 v26, v18 offset:1036
	s_waitcnt lgkmcnt(4)
	v_lshl_or_b32 v21, v22, 16, v21
	v_lshl_or_b32 v20, v20, 16, v19
	s_waitcnt lgkmcnt(2)
	v_lshl_or_b32 v22, v24, 16, v23
	v_or_b32_e32 v24, s10, v16
	s_waitcnt lgkmcnt(0)
	v_lshl_or_b32 v23, v26, 16, v25
	v_ashrrev_i32_e32 v25, 31, v24
	v_lshlrev_b64 v[24:25], 10, v[24:25]
	v_lshl_add_u64 v[24:25], s[0:1], 0, v[24:25]
	v_lshl_add_u64 v[24:25], v[24:25], 0, v[98:99]
	global_store_dwordx4 v[24:25], v[20:23], off
	s_waitcnt lgkmcnt(0)
	s_cbranch_scc1 .LBB0_737

.LBB0_803:
	s_lshl_b32 s0, s4, 11
	s_and_b32 s7, s4, 31
	v_mov_b32_e32 v78, v0
	s_and_b32 s0, s0, 0x3800
	v_readlane_b32 s1, v252, 2
	s_add_u32 s0, s1, s0
	v_and_b32_e32 v80, 15, v78
	v_readlane_b32 s1, v252, 3
	s_addc_u32 s1, s1, 0
	v_lshlrev_b32_e32 v98, 7, v80
	s_waitcnt lgkmcnt(0)
	v_lshl_add_u64 v[2:3], s[0:1], 0, v[98:99]
	v_readlane_b32 s0, v251, 62
	v_lshlrev_b32_e32 v10, 4, v80
	v_mov_b32_e32 v11, v99
	v_readlane_b32 s1, v251, 63
	v_readlane_b32 s10, v254, 15
	v_ashrrev_i32_e32 v17, 4, v78
	v_bfe_u32 v81, v78, 4, 2
	v_lshl_add_u64 v[14:15], s[0:1], 0, v[10:11]
	v_add_u32_e32 v16, s10, v10
	v_lshlrev_b32_e32 v10, 7, v17
	v_lshlrev_b32_e32 v74, 4, v81
	v_mov_b32_e32 v75, v99
	v_ashrrev_i32_e32 v11, 31, v10
	v_lshl_add_u64 v[2:3], v[2:3], 0, v[74:75]
	v_lshl_add_u64 v[10:11], v[10:11], 1, v[14:15]
	global_load_dwordx4 v[6:9], v[2:3], off
	s_nop 0
	global_load_dwordx4 v[2:5], v[2:3], off offset:64
	v_mul_lo_u32 v17, v17, s31
	global_load_dwordx4 v[100:103], v[10:11], off
	v_add_u32_e32 v18, v16, v17
	v_add_u32_e32 v20, 0x200, v78
	v_readlane_b32 s11, v254, 16
	v_ashrrev_i32_e32 v82, 6, v78
	v_readlane_b32 s8, v252, 0
	v_readlane_b32 s9, v252, 1
	v_lshrrev_b32_e32 v83, 4, v78
	v_lshlrev_b32_e32 v79, 6, v80
	v_mov_b32_e32 v124, v18
	v_ashrrev_i32_e32 v18, 4, v20
	v_lshlrev_b32_e32 v10, 7, v18
	v_ashrrev_i32_e32 v11, 31, v10
	v_lshl_add_u64 v[10:11], v[10:11], 1, v[14:15]
	global_load_dwordx4 v[104:107], v[10:11], off
	v_mul_lo_u32 v21, v18, s31
	v_add_u32_e32 v18, v16, v21
	v_mov_b32_e32 v125, v18
	v_add_u32_e32 v10, 0x400, v78
	v_ashrrev_i32_e32 v18, 4, v10
	v_lshlrev_b32_e32 v10, 7, v18
	v_ashrrev_i32_e32 v11, 31, v10
	v_lshl_add_u64 v[10:11], v[10:11], 1, v[14:15]
	global_load_dwordx4 v[108:111], v[10:11], off
	v_mad_u64_u32 v[18:19], s[0:1], v18, s31, v[16:17]
	v_mov_b32_e32 v126, v18
	v_add_u32_e32 v10, 0x600, v78
	v_ashrrev_i32_e32 v18, 4, v10
	v_lshlrev_b32_e32 v10, 7, v18
	v_ashrrev_i32_e32 v11, 31, v10
	v_lshl_add_u64 v[10:11], v[10:11], 1, v[14:15]
	global_load_dwordx4 v[112:115], v[10:11], off
	v_mad_u64_u32 v[14:15], s[0:1], v18, s31, v[16:17]
	v_readlane_b32 s0, v252, 4
	v_readlane_b32 s1, v252, 5
	v_mov_b32_e32 v127, v14
	v_lshlrev_b32_e32 v10, 4, v78
	v_lshlrev_b32_e32 v14, 2, v78
	v_and_b32_e32 v10, 0xf0, v10
	v_ashrrev_i32_e32 v15, 31, v14
	v_add_u32_e32 v16, s11, v10
	v_lshl_add_u64 v[10:11], v[14:15], 2, s[0:1]
	global_load_dwordx4 v[116:119], v[10:11], off
	v_add_u32_e32 v15, v16, v17
	v_mov_b32_e32 v128, v15
	v_lshlrev_b32_e32 v10, 2, v20
	v_ashrrev_i32_e32 v11, 31, v10
	v_lshl_add_u64 v[10:11], v[10:11], 2, s[0:1]
	global_load_dwordx4 v[120:123], v[10:11], off
	v_add_u32_e32 v15, v16, v21
	s_and_b32 s1, s2, 0xfffff800
	s_lshl_b32 s0, s7, 4
	s_and_b32 s68, s0, 0x180
	v_mov_b32_e32 v129, v15
	s_waitcnt vmcnt(0)
	ds_write_b128 v124, v[100:103]
	ds_write_b128 v125, v[104:107]
	ds_write_b128 v126, v[108:111]
	ds_write_b128 v127, v[112:115]
	ds_write_b128 v128, v[116:119]
	ds_write_b128 v129, v[120:123]
	v_or_b32_e32 v11, s1, v80
	v_lshlrev_b32_e32 v12, 3, v78
	v_lshl_add_u32 v76, v82, 8, v11
	v_lshlrev_b32_e32 v10, 4, v82
	v_and_b32_e32 v84, 0x80, v12
	v_and_b32_e32 v12, 0x80, v14
	v_ashrrev_i32_e32 v77, 31, v76
	v_add3_u32 v85, 0, v10, v12
	v_lshlrev_b64 v[10:11], 12, v[76:77]
	v_lshl_add_u64 v[10:11], s[86:87], 0, v[10:11]
	v_lshl_add_u64 v[10:11], v[10:11], 0, s[68:69]
	v_lshl_add_u64 v[10:11], v[10:11], 0, v[74:75]
	v_lshl_add_u64 v[12:13], v[10:11], 0, s[34:35]
	v_add_co_u32_e32 v10, vcc, s95, v10
	v_or_b32_e32 v14, 0x50, v76
	s_nop 0
	v_addc_co_u32_e32 v11, vcc, 0, v11, vcc
	global_load_dwordx4 v[70:73], v[10:11], off offset:1536
	global_load_dwordx4 v[62:65], v[12:13], off offset:64
	v_or_b32_e32 v10, 16, v76
	v_ashrrev_i32_e32 v11, 31, v10
	v_lshlrev_b64 v[10:11], 12, v[10:11]
	v_lshl_add_u64 v[10:11], s[86:87], 0, v[10:11]
	v_lshl_add_u64 v[10:11], v[10:11], 0, s[68:69]
	v_lshl_add_u64 v[10:11], v[10:11], 0, v[74:75]
	v_lshl_add_u64 v[12:13], v[10:11], 0, s[34:35]
	v_add_co_u32_e32 v10, vcc, s95, v10
	v_ashrrev_i32_e32 v15, 31, v14
	s_nop 0
	v_addc_co_u32_e32 v11, vcc, 0, v11, vcc
	global_load_dwordx4 v[66:69], v[10:11], off offset:1536
	global_load_dwordx4 v[54:57], v[12:13], off offset:64
	v_or_b32_e32 v10, 32, v76
	v_ashrrev_i32_e32 v11, 31, v10
	v_lshlrev_b64 v[10:11], 12, v[10:11]
	v_lshl_add_u64 v[10:11], s[86:87], 0, v[10:11]
	v_lshl_add_u64 v[10:11], v[10:11], 0, s[68:69]
	v_lshl_add_u64 v[10:11], v[10:11], 0, v[74:75]
	v_lshl_add_u64 v[12:13], v[10:11], 0, s[34:35]
	v_add_co_u32_e32 v10, vcc, s95, v10
	v_lshlrev_b64 v[14:15], 12, v[14:15]
	s_nop 0
	v_addc_co_u32_e32 v11, vcc, 0, v11, vcc
	global_load_dwordx4 v[58:61], v[10:11], off offset:1536
	global_load_dwordx4 v[38:41], v[12:13], off offset:64
	v_or_b32_e32 v10, 48, v76
	v_ashrrev_i32_e32 v11, 31, v10
	v_lshlrev_b64 v[10:11], 12, v[10:11]
	v_lshl_add_u64 v[10:11], s[86:87], 0, v[10:11]
	v_lshl_add_u64 v[10:11], v[10:11], 0, s[68:69]
	v_lshl_add_u64 v[10:11], v[10:11], 0, v[74:75]
	v_lshl_add_u64 v[12:13], v[10:11], 0, s[34:35]
	v_add_co_u32_e32 v10, vcc, s95, v10
	v_lshl_add_u64 v[14:15], s[86:87], 0, v[14:15]
	s_nop 0
	v_addc_co_u32_e32 v11, vcc, 0, v11, vcc
	global_load_dwordx4 v[50:53], v[10:11], off offset:1536
	global_load_dwordx4 v[22:25], v[12:13], off offset:64
	v_or_b32_e32 v10, 64, v76
	v_ashrrev_i32_e32 v11, 31, v10
	v_lshlrev_b64 v[10:11], 12, v[10:11]
	v_lshl_add_u64 v[10:11], s[86:87], 0, v[10:11]
	v_lshl_add_u64 v[10:11], v[10:11], 0, s[68:69]
	v_lshl_add_u64 v[10:11], v[10:11], 0, v[74:75]
	v_lshl_add_u64 v[12:13], v[10:11], 0, s[34:35]
	v_add_co_u32_e32 v10, vcc, s95, v10
	v_lshl_add_u64 v[14:15], v[14:15], 0, s[68:69]
	v_or_b32_e32 v30, 0x60, v76
	v_addc_co_u32_e32 v11, vcc, 0, v11, vcc
	v_lshl_add_u64 v[14:15], v[14:15], 0, v[74:75]
	v_ashrrev_i32_e32 v31, 31, v30
	v_lshl_add_u64 v[18:19], v[14:15], 0, s[34:35]
	v_add_co_u32_e32 v14, vcc, s95, v14
	v_lshlrev_b64 v[30:31], 12, v[30:31]
	s_nop 0
	v_addc_co_u32_e32 v15, vcc, 0, v15, vcc
	v_lshl_add_u64 v[30:31], s[86:87], 0, v[30:31]
	global_load_dwordx4 v[26:29], v[10:11], off offset:1536
	s_nop 0
	global_load_dwordx4 v[10:13], v[12:13], off offset:64
	s_nop 0
	global_load_dwordx4 v[14:17], v[14:15], off offset:1536
	s_nop 0
	global_load_dwordx4 v[18:21], v[18:19], off offset:64
	v_lshl_add_u64 v[30:31], v[30:31], 0, s[68:69]
	v_lshl_add_u64 v[30:31], v[30:31], 0, v[74:75]
	v_lshl_add_u64 v[34:35], v[30:31], 0, s[34:35]
	v_add_co_u32_e32 v30, vcc, s95, v30
	v_or_b32_e32 v42, 0x70, v76
	s_nop 0
	v_addc_co_u32_e32 v31, vcc, 0, v31, vcc
	global_load_dwordx4 v[30:33], v[30:31], off offset:1536
	s_nop 0
	global_load_dwordx4 v[34:37], v[34:35], off offset:64
	v_ashrrev_i32_e32 v43, 31, v42
	v_lshlrev_b64 v[42:43], 12, v[42:43]
	v_lshl_add_u64 v[42:43], s[86:87], 0, v[42:43]
	v_lshl_add_u64 v[42:43], v[42:43], 0, s[68:69]
	v_lshl_add_u64 v[42:43], v[42:43], 0, v[74:75]
	v_lshl_add_u64 v[46:47], v[42:43], 0, s[34:35]
	v_add_co_u32_e32 v42, vcc, s95, v42
	s_waitcnt vmcnt(3)
	v_mfma_f32_16x16x32_bf16 v[14:17], v[6:9], v[14:17], 0
	v_addc_co_u32_e32 v43, vcc, 0, v43, vcc
	global_load_dwordx4 v[42:45], v[42:43], off offset:1536
	s_nop 0
	global_load_dwordx4 v[46:49], v[46:47], off offset:64
	v_mfma_f32_16x16x32_bf16 v[26:29], v[6:9], v[26:29], 0
	s_waitcnt vmcnt(4)
	v_mfma_f32_16x16x32_bf16 v[14:17], v[2:5], v[18:21], v[14:17]
	s_waitcnt vmcnt(3)
	v_mfma_f32_16x16x32_bf16 v[18:21], v[6:9], v[30:33], 0
	v_mfma_f32_16x16x32_bf16 v[70:73], v[6:9], v[70:73], 0
	v_mfma_f32_16x16x32_bf16 v[58:61], v[6:9], v[58:61], 0
	v_mfma_f32_16x16x32_bf16 v[10:13], v[2:5], v[10:13], v[26:29]
	s_waitcnt vmcnt(2)
	v_mfma_f32_16x16x32_bf16 v[18:21], v[2:5], v[34:37], v[18:21]
	v_mfma_f32_16x16x32_bf16 v[62:65], v[2:5], v[62:65], v[70:73]
	v_mfma_f32_16x16x32_bf16 v[38:41], v[2:5], v[38:41], v[58:61]
	s_nop 5
	v_cvt_pk_bf16_f32 v31, v10, v18
	v_or_b32_e32 v18, 32, v84
	v_or_b32_e32 v10, v84, v80
	s_waitcnt vmcnt(1)
	v_mfma_f32_16x16x32_bf16 v[26:29], v[6:9], v[42:45], 0
	v_cvt_pk_bf16_f32 v11, v11, v19
	v_or_b32_e32 v19, v18, v80
	v_cvt_pk_bf16_f32 v30, v62, v38
	v_mfma_f32_16x16x32_bf16 v[66:69], v[6:9], v[66:69], 0
	v_mad_u32_u24 v38, v10, s31, v85
	v_cvt_pk_bf16_f32 v10, v63, v39
	v_mad_u32_u24 v39, v19, s31, v85
	v_mfma_f32_16x16x32_bf16 v[50:53], v[6:9], v[50:53], 0
	ds_write_b64 v38, v[30:31]
	ds_write_b64 v39, v[10:11]
	v_cvt_pk_bf16_f32 v11, v12, v20
	v_or_b32_e32 v12, 64, v84
	v_or_b32_e32 v19, v12, v80
	s_waitcnt vmcnt(0)
	v_mfma_f32_16x16x32_bf16 v[26:29], v[2:5], v[46:49], v[26:29]
	v_cvt_pk_bf16_f32 v10, v64, v40
	v_mad_u32_u24 v40, v19, s31, v85
	ds_write_b64 v40, v[10:11]
	v_mfma_f32_16x16x32_bf16 v[54:57], v[2:5], v[54:57], v[66:69]
	v_cvt_pk_bf16_f32 v11, v13, v21
	v_or_b32_e32 v13, 0x60, v84
	v_or_b32_e32 v19, v13, v80
	v_mfma_f32_16x16x32_bf16 v[22:25], v[2:5], v[22:25], v[50:53]
	v_cvt_pk_bf16_f32 v10, v65, v41
	v_mad_u32_u24 v41, v19, s31, v85
	v_or_b32_e32 v72, 16, v80
	ds_write_b64 v41, v[10:11]
	v_cvt_pk_bf16_f32 v11, v14, v26
	v_or_b32_e32 v14, v84, v72
	s_nop 1
	v_cvt_pk_bf16_f32 v10, v54, v22
	v_mad_u32_u24 v42, v14, s31, v85
	v_or_b32_e32 v14, v18, v72
	ds_write_b64 v42, v[10:11]
	v_cvt_pk_bf16_f32 v10, v55, v23
	v_cvt_pk_bf16_f32 v11, v15, v27
	v_mad_u32_u24 v43, v14, s31, v85
	v_or_b32_e32 v12, v12, v72
	ds_write_b64 v43, v[10:11]
	v_cvt_pk_bf16_f32 v10, v56, v24
	v_cvt_pk_bf16_f32 v11, v16, v28
	v_mad_u32_u24 v44, v12, s31, v85
	v_or_b32_e32 v12, v13, v72
	ds_write_b64 v44, v[10:11]
	v_cvt_pk_bf16_f32 v10, v57, v25
	v_cvt_pk_bf16_f32 v11, v17, v29
	v_mad_u32_u24 v45, v12, s31, v85
	ds_write_b64 v45, v[10:11]
	v_or_b32_e32 v10, 0x80, v76
	v_ashrrev_i32_e32 v11, 31, v10
	v_lshlrev_b64 v[10:11], 12, v[10:11]
	v_lshl_add_u64 v[10:11], s[86:87], 0, v[10:11]
	v_lshl_add_u64 v[10:11], v[10:11], 0, s[68:69]
	v_lshl_add_u64 v[10:11], v[10:11], 0, v[74:75]
	v_lshl_add_u64 v[12:13], v[10:11], 0, s[34:35]
	v_add_co_u32_e32 v10, vcc, s95, v10
	v_or_b32_e32 v14, 0xf0, v76
	s_nop 0
	v_addc_co_u32_e32 v11, vcc, 0, v11, vcc
	global_load_dwordx4 v[46:49], v[10:11], off offset:1536
	global_load_dwordx4 v[50:53], v[12:13], off offset:64
	v_or_b32_e32 v10, 0x90, v76
	v_ashrrev_i32_e32 v11, 31, v10
	v_lshlrev_b64 v[10:11], 12, v[10:11]
	v_lshl_add_u64 v[10:11], s[86:87], 0, v[10:11]
	v_lshl_add_u64 v[10:11], v[10:11], 0, s[68:69]
	v_lshl_add_u64 v[10:11], v[10:11], 0, v[74:75]
	v_lshl_add_u64 v[12:13], v[10:11], 0, s[34:35]
	v_add_co_u32_e32 v10, vcc, s95, v10
	v_ashrrev_i32_e32 v15, 31, v14
	s_nop 0
	v_addc_co_u32_e32 v11, vcc, 0, v11, vcc
	global_load_dwordx4 v[54:57], v[10:11], off offset:1536
	global_load_dwordx4 v[58:61], v[12:13], off offset:64
	v_or_b32_e32 v10, 0xa0, v76
	v_ashrrev_i32_e32 v11, 31, v10
	v_lshlrev_b64 v[10:11], 12, v[10:11]
	v_lshl_add_u64 v[10:11], s[86:87], 0, v[10:11]
	v_lshl_add_u64 v[10:11], v[10:11], 0, s[68:69]
	v_lshl_add_u64 v[10:11], v[10:11], 0, v[74:75]
	v_lshl_add_u64 v[12:13], v[10:11], 0, s[34:35]
	v_add_co_u32_e32 v10, vcc, s95, v10
	v_lshlrev_b64 v[14:15], 12, v[14:15]
	s_nop 0
	v_addc_co_u32_e32 v11, vcc, 0, v11, vcc
	global_load_dwordx4 v[62:65], v[10:11], off offset:1536
	global_load_dwordx4 v[66:69], v[12:13], off offset:64
	v_or_b32_e32 v10, 0xb0, v76
	v_ashrrev_i32_e32 v11, 31, v10
	v_lshlrev_b64 v[10:11], 12, v[10:11]
	v_lshl_add_u64 v[10:11], s[86:87], 0, v[10:11]
	v_lshl_add_u64 v[10:11], v[10:11], 0, s[68:69]
	v_lshl_add_u64 v[10:11], v[10:11], 0, v[74:75]
	v_lshl_add_u64 v[12:13], v[10:11], 0, s[34:35]
	v_add_co_u32_e32 v10, vcc, s95, v10
	v_lshl_add_u64 v[14:15], s[86:87], 0, v[14:15]
	s_nop 0
	v_addc_co_u32_e32 v11, vcc, 0, v11, vcc
	global_load_dwordx4 v[84:87], v[10:11], off offset:1536
	global_load_dwordx4 v[88:91], v[12:13], off offset:64
	v_or_b32_e32 v10, 0xc0, v76
	v_ashrrev_i32_e32 v11, 31, v10
	v_lshlrev_b64 v[10:11], 12, v[10:11]
	v_lshl_add_u64 v[10:11], s[86:87], 0, v[10:11]
	v_lshl_add_u64 v[10:11], v[10:11], 0, s[68:69]
	v_lshl_add_u64 v[10:11], v[10:11], 0, v[74:75]
	v_lshl_add_u64 v[12:13], v[10:11], 0, s[34:35]
	v_add_co_u32_e32 v10, vcc, s95, v10
	v_lshl_add_u64 v[14:15], v[14:15], 0, s[68:69]
	s_nop 0
	v_addc_co_u32_e32 v11, vcc, 0, v11, vcc
	global_load_dwordx4 v[92:95], v[10:11], off offset:1536
	global_load_dwordx4 v[30:33], v[12:13], off offset:64
	v_or_b32_e32 v10, 0xd0, v76
	v_ashrrev_i32_e32 v11, 31, v10
	v_lshlrev_b64 v[10:11], 12, v[10:11]
	v_lshl_add_u64 v[10:11], s[86:87], 0, v[10:11]
	v_lshl_add_u64 v[10:11], v[10:11], 0, s[68:69]
	v_lshl_add_u64 v[10:11], v[10:11], 0, v[74:75]
	v_lshl_add_u64 v[12:13], v[10:11], 0, s[34:35]
	v_add_co_u32_e32 v10, vcc, s95, v10
	v_lshl_add_u64 v[14:15], v[14:15], 0, v[74:75]
	s_nop 0
	v_addc_co_u32_e32 v11, vcc, 0, v11, vcc
	global_load_dwordx4 v[34:37], v[10:11], off offset:1536
	global_load_dwordx4 v[22:25], v[12:13], off offset:64
	v_or_b32_e32 v10, 0xe0, v76
	v_ashrrev_i32_e32 v11, 31, v10
	v_lshlrev_b64 v[10:11], 12, v[10:11]
	v_lshl_add_u64 v[10:11], s[86:87], 0, v[10:11]
	v_lshl_add_u64 v[10:11], v[10:11], 0, s[68:69]
	v_lshl_add_u64 v[10:11], v[10:11], 0, v[74:75]
	v_lshl_add_u64 v[12:13], v[10:11], 0, s[34:35]
	v_add_co_u32_e32 v10, vcc, s95, v10
	v_lshl_add_u64 v[18:19], v[14:15], 0, s[34:35]
	s_nop 0
	v_addc_co_u32_e32 v11, vcc, 0, v11, vcc
	global_load_dwordx4 v[26:29], v[10:11], off offset:1536
	s_nop 0
	global_load_dwordx4 v[10:13], v[12:13], off offset:64
	v_add_co_u32_e32 v14, vcc, s95, v14
	s_waitcnt vmcnt(13)
	v_mfma_f32_16x16x32_bf16 v[46:49], v[6:9], v[46:49], 0
	v_addc_co_u32_e32 v15, vcc, 0, v15, vcc
	global_load_dwordx4 v[14:17], v[14:15], off offset:1536
	s_nop 0
	global_load_dwordx4 v[18:21], v[18:19], off offset:64
	s_waitcnt vmcnt(14)
	v_mfma_f32_16x16x32_bf16 v[46:49], v[2:5], v[50:53], v[46:49]
	s_waitcnt vmcnt(13)
	v_mfma_f32_16x16x32_bf16 v[50:53], v[6:9], v[54:57], 0
	s_waitcnt vmcnt(11)
	v_mfma_f32_16x16x32_bf16 v[54:57], v[6:9], v[62:65], 0
	s_waitcnt vmcnt(7)
	v_mfma_f32_16x16x32_bf16 v[62:65], v[6:9], v[92:95], 0
	s_waitcnt vmcnt(3)
	v_mfma_f32_16x16x32_bf16 v[26:29], v[6:9], v[26:29], 0
	v_mfma_f32_16x16x32_bf16 v[50:53], v[2:5], v[58:61], v[50:53]
	v_mfma_f32_16x16x32_bf16 v[54:57], v[2:5], v[66:69], v[54:57]
	v_mfma_f32_16x16x32_bf16 v[58:61], v[6:9], v[84:87], 0
	v_mfma_f32_16x16x32_bf16 v[30:33], v[2:5], v[30:33], v[62:65]
	v_mfma_f32_16x16x32_bf16 v[34:37], v[6:9], v[34:37], 0
	s_waitcnt vmcnt(2)
	v_mfma_f32_16x16x32_bf16 v[10:13], v[2:5], v[10:13], v[26:29]
	s_waitcnt vmcnt(1)
	v_mfma_f32_16x16x32_bf16 v[6:9], v[6:9], v[14:17], 0
	v_mfma_f32_16x16x32_bf16 v[58:61], v[2:5], v[88:91], v[58:61]
	v_mfma_f32_16x16x32_bf16 v[22:25], v[2:5], v[22:25], v[34:37]
	s_waitcnt vmcnt(0)
	v_mfma_f32_16x16x32_bf16 v[2:5], v[2:5], v[18:21], v[6:9]
	v_lshl_or_b32 v18, v82, 5, v80
	v_mul_lo_u32 v18, v18, s31
	v_mov_b32_e32 v36, 0x1100
	s_nop 0
	v_cvt_pk_bf16_f32 v6, v46, v54
	v_cvt_pk_bf16_f32 v7, v30, v10
	ds_write_b64 v38, v[6:7] offset:8
	v_cvt_pk_bf16_f32 v6, v47, v55
	v_cvt_pk_bf16_f32 v7, v31, v11
	ds_write_b64 v39, v[6:7] offset:8
	v_cvt_pk_bf16_f32 v6, v48, v56
	v_cvt_pk_bf16_f32 v7, v32, v12
	ds_write_b64 v40, v[6:7] offset:8
	v_cvt_pk_bf16_f32 v6, v49, v57
	v_cvt_pk_bf16_f32 v7, v33, v13
	ds_write_b64 v41, v[6:7] offset:8
	v_cvt_pk_bf16_f32 v6, v50, v58
	v_cvt_pk_bf16_f32 v7, v22, v2
	v_cvt_pk_bf16_f32 v2, v51, v59
	v_cvt_pk_bf16_f32 v3, v23, v3
	ds_write_b64 v42, v[6:7] offset:8
	ds_write_b64 v43, v[2:3] offset:8
	v_cvt_pk_bf16_f32 v2, v52, v60
	v_cvt_pk_bf16_f32 v3, v24, v4
	ds_write_b64 v44, v[2:3] offset:8
	v_cvt_pk_bf16_f32 v2, v53, v61
	v_cvt_pk_bf16_f32 v3, v25, v5
	v_mov_b32_e32 v44, 0x2200
	v_mov_b32_e32 v53, 0x3300
	ds_write_b64 v45, v[2:3] offset:8
	v_lshl_add_u64 v[2:3], s[8:9], 0, v[74:75]
	v_add3_u32 v31, 0, v18, v74
	v_add_u32_e32 v52, s10, v74
	v_mad_u32_u24 v75, v80, s31, v36
	v_mad_u32_u24 v74, v80, s31, v44
	v_mad_u32_u24 v73, v80, s31, v53
	v_lshl_add_u64 v[2:3], v[2:3], 0, v[98:99]
	v_mad_u32_u24 v30, v80, s31, v52
	v_add_u32_e32 v76, v52, v75
	v_add_u32_e32 v77, v52, v74
	v_add_u32_e32 v96, v52, v73
	global_load_dwordx4 v[10:13], v[2:3], off
	global_load_dwordx4 v[6:9], v[2:3], off offset:64
	global_load_dwordx4 v[14:17], v[2:3], off offset:2048
	s_nop 0
	global_load_dwordx4 v[2:5], v[2:3], off offset:2112
	s_waitcnt lgkmcnt(0)
	s_barrier
	ds_read_b128 v[18:21], v31
	ds_read_b128 v[22:25], v31 offset:4352
	ds_read_b128 v[26:29], v30
	ds_read_b128 v[60:63], v30 offset:17408
	ds_read_b128 v[36:39], v76
	ds_read_b128 v[100:103], v30 offset:30464
	ds_read_b128 v[44:47], v77
	ds_read_b128 v[52:55], v96
	ds_read_b128 v[68:71], v30 offset:21760
	ds_read_b128 v[88:91], v30 offset:26112
	s_waitcnt lgkmcnt(7)
	v_mfma_f32_16x16x32_bf16 v[32:35], v[18:21], v[26:29], 0
	s_movk_i32 s10, 0x90
	v_bfe_u32 v98, v78, 1, 3
	v_mfma_f32_16x16x32_bf16 v[26:29], v[22:25], v[26:29], 0
	s_waitcnt lgkmcnt(5)
	v_mfma_f32_16x16x32_bf16 v[40:43], v[18:21], v[36:39], 0
	v_mfma_f32_16x16x32_bf16 v[36:39], v[22:25], v[36:39], 0
	s_waitcnt lgkmcnt(3)
	v_mfma_f32_16x16x32_bf16 v[48:51], v[18:21], v[44:47], 0
	v_mfma_f32_16x16x32_bf16 v[44:47], v[22:25], v[44:47], 0
	s_waitcnt lgkmcnt(2)
	v_mfma_f32_16x16x32_bf16 v[56:59], v[18:21], v[52:55], 0
	v_mfma_f32_16x16x32_bf16 v[52:55], v[22:25], v[52:55], 0
	v_mfma_f32_16x16x32_bf16 v[64:67], v[18:21], v[60:63], 0
	v_mfma_f32_16x16x32_bf16 v[60:63], v[22:25], v[60:63], 0
	s_waitcnt lgkmcnt(1)
	v_mfma_f32_16x16x32_bf16 v[84:87], v[18:21], v[68:71], 0
	v_mfma_f32_16x16x32_bf16 v[68:71], v[22:25], v[68:71], 0
	s_waitcnt lgkmcnt(0)
	v_mfma_f32_16x16x32_bf16 v[92:95], v[18:21], v[88:91], 0
	v_mfma_f32_16x16x32_bf16 v[88:91], v[22:25], v[88:91], 0
	v_mfma_f32_16x16x32_bf16 v[18:21], v[18:21], v[100:103], 0
	v_mfma_f32_16x16x32_bf16 v[22:25], v[22:25], v[100:103], 0
	ds_read_b128 v[100:103], v31 offset:64
	ds_read_b128 v[104:107], v31 offset:4416
	ds_read_b128 v[108:111], v30 offset:64
	s_waitcnt lgkmcnt(0)
	v_mfma_f32_16x16x32_bf16 v[32:35], v[100:103], v[108:111], v[32:35]
	v_mfma_f32_16x16x32_bf16 v[26:29], v[104:107], v[108:111], v[26:29]
	ds_read_b128 v[108:111], v76 offset:64
	s_waitcnt lgkmcnt(0)
	v_mfma_f32_16x16x32_bf16 v[40:43], v[100:103], v[108:111], v[40:43]
	v_mfma_f32_16x16x32_bf16 v[36:39], v[104:107], v[108:111], v[36:39]
	ds_read_b128 v[108:111], v77 offset:64
	s_waitcnt lgkmcnt(0)
	v_mfma_f32_16x16x32_bf16 v[48:51], v[100:103], v[108:111], v[48:51]
	v_mfma_f32_16x16x32_bf16 v[44:47], v[104:107], v[108:111], v[44:47]
	ds_read_b128 v[108:111], v96 offset:64
	s_waitcnt lgkmcnt(0)
	v_mfma_f32_16x16x32_bf16 v[56:59], v[100:103], v[108:111], v[56:59]
	v_mfma_f32_16x16x32_bf16 v[52:55], v[104:107], v[108:111], v[52:55]
	ds_read_b128 v[108:111], v30 offset:17472
	s_waitcnt lgkmcnt(0)
	v_mfma_f32_16x16x32_bf16 v[64:67], v[100:103], v[108:111], v[64:67]
	v_mfma_f32_16x16x32_bf16 v[60:63], v[104:107], v[108:111], v[60:63]
	ds_read_b128 v[108:111], v30 offset:21824
	s_waitcnt lgkmcnt(0)
	v_mfma_f32_16x16x32_bf16 v[84:87], v[100:103], v[108:111], v[84:87]
	v_mfma_f32_16x16x32_bf16 v[68:71], v[104:107], v[108:111], v[68:71]
	ds_read_b128 v[108:111], v30 offset:26176
	s_waitcnt lgkmcnt(0)
	v_mfma_f32_16x16x32_bf16 v[92:95], v[100:103], v[108:111], v[92:95]
	v_mfma_f32_16x16x32_bf16 v[88:91], v[104:107], v[108:111], v[88:91]
	ds_read_b128 v[108:111], v30 offset:30528
	s_waitcnt lgkmcnt(0)
	v_mfma_f32_16x16x32_bf16 v[18:21], v[100:103], v[108:111], v[18:21]
	v_mfma_f32_16x16x32_bf16 v[22:25], v[104:107], v[108:111], v[22:25]
	ds_read_b128 v[100:103], v31 offset:128
	ds_read_b128 v[104:107], v31 offset:4480
	ds_read_b128 v[108:111], v30 offset:128
	s_waitcnt lgkmcnt(0)
	v_mfma_f32_16x16x32_bf16 v[32:35], v[100:103], v[108:111], v[32:35]
	v_mfma_f32_16x16x32_bf16 v[26:29], v[104:107], v[108:111], v[26:29]
	ds_read_b128 v[108:111], v76 offset:128
	s_waitcnt lgkmcnt(0)
	v_mfma_f32_16x16x32_bf16 v[40:43], v[100:103], v[108:111], v[40:43]
	v_mfma_f32_16x16x32_bf16 v[36:39], v[104:107], v[108:111], v[36:39]
	ds_read_b128 v[108:111], v77 offset:128
	s_waitcnt lgkmcnt(0)
	v_mfma_f32_16x16x32_bf16 v[112:115], v[100:103], v[108:111], v[48:51]
	v_mfma_f32_16x16x32_bf16 v[46:49], v[104:107], v[108:111], v[44:47]
	ds_read_b128 v[108:111], v96 offset:128
	s_waitcnt lgkmcnt(0)
	v_mfma_f32_16x16x32_bf16 v[56:59], v[100:103], v[108:111], v[56:59]
	v_mfma_f32_16x16x32_bf16 v[108:111], v[104:107], v[108:111], v[52:55]
	s_nop 2
	ds_read_b128 v[50:53], v30 offset:17536
	s_waitcnt lgkmcnt(0)
	v_mfma_f32_16x16x32_bf16 v[116:119], v[100:103], v[50:53], v[64:67]
	v_mfma_f32_16x16x32_bf16 v[120:123], v[104:107], v[50:53], v[60:63]
	ds_read_b128 v[50:53], v30 offset:21888
	s_waitcnt lgkmcnt(0)
	v_mfma_f32_16x16x32_bf16 v[84:87], v[100:103], v[50:53], v[84:87]
	v_mfma_f32_16x16x32_bf16 v[124:127], v[104:107], v[50:53], v[68:71]
	ds_read_b128 v[50:53], v30 offset:26240
	s_waitcnt lgkmcnt(0)
	v_mfma_f32_16x16x32_bf16 v[92:95], v[100:103], v[50:53], v[92:95]
	v_mfma_f32_16x16x32_bf16 v[88:91], v[104:107], v[50:53], v[88:91]
	ds_read_b128 v[50:53], v30 offset:30592
	s_waitcnt lgkmcnt(0)
	v_mfma_f32_16x16x32_bf16 v[100:103], v[100:103], v[50:53], v[18:21]
	ds_read_b128 v[128:131], v31 offset:192
	ds_read_b128 v[132:135], v31 offset:4544
	s_nop 0
	ds_read_b128 v[18:21], v30 offset:192
	s_waitcnt lgkmcnt(0)
	v_mfma_f32_16x16x32_bf16 v[136:139], v[128:131], v[18:21], v[32:35]
	v_mfma_f32_16x16x32_bf16 v[62:65], v[132:135], v[18:21], v[26:29]
	ds_read_b128 v[18:21], v76 offset:192
	v_bfe_u32 v76, v83, 1, 1
	v_mfma_f32_16x16x32_bf16 v[104:107], v[104:107], v[50:53], v[22:25]
	s_waitcnt lgkmcnt(0)
	v_mfma_f32_16x16x32_bf16 v[50:53], v[128:131], v[18:21], v[40:43]
	v_mfma_f32_16x16x32_bf16 v[42:45], v[132:135], v[18:21], v[36:39]
	ds_read_b128 v[18:21], v77 offset:192
	s_nop 1
	ds_read_b128 v[38:41], v30 offset:17600
	s_waitcnt lgkmcnt(1)
	v_mfma_f32_16x16x32_bf16 v[34:37], v[128:131], v[18:21], v[112:115]
	v_lshl_add_u32 v77, v81, 5, s11
	v_mad_u32_u24 v83, v80, s31, v77
	v_add_u32_e32 v75, v77, v75
	v_mfma_f32_16x16x32_bf16 v[26:29], v[132:135], v[18:21], v[46:49]
	ds_read_b128 v[18:21], v96 offset:192
	s_waitcnt lgkmcnt(0)
	v_mfma_f32_16x16x32_bf16 v[22:25], v[128:131], v[18:21], v[56:59]
	v_mfma_f32_16x16x32_bf16 v[18:21], v[132:135], v[18:21], v[108:111]
	v_mfma_f32_16x16x32_bf16 v[108:111], v[128:131], v[38:41], v[116:119]
	v_mfma_f32_16x16x32_bf16 v[112:115], v[132:135], v[38:41], v[120:123]
	ds_read_b128 v[38:41], v30 offset:21952
	s_waitcnt lgkmcnt(0)
	v_mfma_f32_16x16x32_bf16 v[66:69], v[128:131], v[38:41], v[84:87]
	v_mfma_f32_16x16x32_bf16 v[58:61], v[132:135], v[38:41], v[124:127]
	ds_read_b128 v[38:41], v30 offset:26304
	ds_read_b128 v[30:33], v30 offset:30656
	s_waitcnt lgkmcnt(0)
	v_mfma_f32_16x16x32_bf16 v[46:49], v[132:135], v[38:41], v[88:91]
	s_barrier
	ds_read_b128 v[84:87], v83
	s_nop 0
	ds_read_b128 v[88:91], v83 offset:16
	v_mfma_f32_16x16x32_bf16 v[54:57], v[128:131], v[38:41], v[92:95]
	s_waitcnt lgkmcnt(0)
	v_mov_b32_e32 v97, v90
	s_nop 0
	v_lshrrev_b32_e32 v93, 1, v78
	v_mov_b32_e32 v95, v86
	v_mov_b32_e32 v86, v85
	v_mov_b32_e32 v90, v89
	v_and_b32_e32 v70, 8, v93
	v_mov_b32_e32 v94, v84
	v_pk_mul_f32 v[84:85], v[108:109], v[86:87]
	v_mov_b32_e32 v96, v88
	v_pk_mul_f32 v[88:89], v[110:111], v[90:91]
	v_add_u32_e32 v92, 0, v70
	v_lshl_add_u32 v70, v80, 3, v82
	v_pk_fma_f32 v[84:85], v[136:137], v[94:95], v[84:85] neg_lo:[0,0,1] neg_hi:[0,0,1]
	v_pk_fma_f32 v[88:89], v[138:139], v[96:97], v[88:89] neg_lo:[0,0,1] neg_hi:[0,0,1]
	v_mad_u64_u32 v[70:71], s[8:9], v70, s10, v[92:93]
	v_cvt_pk_bf16_f32 v84, v84, v85
	v_cvt_pk_bf16_f32 v85, v88, v89
	v_pk_mul_f32 v[88:89], v[108:109], v[94:95]
	v_bitop3_b32 v71, v76, v93, 7 bitop3:0x78
	v_pk_fma_f32 v[86:87], v[136:137], v[86:87], v[88:89]
	v_pk_mul_f32 v[88:89], v[110:111], v[96:97]
	v_lshlrev_b32_e32 v71, 4, v71
	v_pk_fma_f32 v[88:89], v[138:139], v[90:91], v[88:89]
	v_cvt_pk_bf16_f32 v86, v86, v87
	v_cvt_pk_bf16_f32 v87, v88, v89
	v_add_u32_e32 v88, v70, v71
	ds_write_b64 v88, v[84:85]
	v_bitop3_b32 v84, v76, v98, 4 bitop3:0x36
	v_mfma_f32_16x16x32_bf16 v[38:41], v[128:131], v[30:33], v[100:103]
	s_nop 2
	v_lshlrev_b32_e32 v100, 4, v84
	v_add_u32_e32 v84, v70, v100
	ds_write_b64 v84, v[86:87]
	ds_read_b128 v[84:87], v83 offset:128
	ds_read_b128 v[88:91], v83 offset:144
	v_mfma_f32_16x16x32_bf16 v[30:33], v[132:135], v[30:33], v[104:107]
	s_waitcnt lgkmcnt(1)
	v_mov_b32_e32 v95, v86
	v_mov_b32_e32 v86, v85
	s_waitcnt lgkmcnt(0)
	v_mov_b32_e32 v97, v90
	v_mov_b32_e32 v90, v89
	v_mov_b32_e32 v94, v84
	v_pk_mul_f32 v[84:85], v[112:113], v[86:87]
	v_mov_b32_e32 v96, v88
	v_pk_mul_f32 v[88:89], v[114:115], v[90:91]
	v_pk_fma_f32 v[84:85], v[62:63], v[94:95], v[84:85] neg_lo:[0,0,1] neg_hi:[0,0,1]
	v_pk_fma_f32 v[88:89], v[64:65], v[96:97], v[88:89] neg_lo:[0,0,1] neg_hi:[0,0,1]
	v_cvt_pk_bf16_f32 v84, v84, v85
	v_cvt_pk_bf16_f32 v85, v88, v89
	v_pk_mul_f32 v[88:89], v[112:113], v[94:95]
	s_nop 0
	v_pk_fma_f32 v[62:63], v[62:63], v[86:87], v[88:89]
	v_pk_mul_f32 v[86:87], v[114:115], v[96:97]
	v_cvt_pk_bf16_f32 v62, v62, v63
	v_pk_fma_f32 v[64:65], v[64:65], v[90:91], v[86:87]
	s_nop 0
	v_cvt_pk_bf16_f32 v63, v64, v65
	v_bitop3_b32 v64, v76, v98, 2 bitop3:0x36
	v_lshlrev_b32_e32 v83, 4, v64
	v_add_u32_e32 v64, v70, v83
	ds_write_b64 v64, v[84:85]
	v_bitop3_b32 v64, v76, v98, 6 bitop3:0x36
	v_lshlrev_b32_e32 v94, 4, v64
	v_add_u32_e32 v64, v70, v94
	ds_write_b64 v64, v[62:63]
	v_lshl_add_u32 v62, v72, 3, v82
	v_mad_u64_u32 v[88:89], s[8:9], v62, s10, v[92:93]
	ds_read_b128 v[62:65], v75
	ds_read_b128 v[84:87], v75 offset:16
	s_waitcnt lgkmcnt(1)
	v_mov_b32_e32 v90, v62
	v_mov_b32_e32 v91, v64
	v_mov_b32_e32 v64, v63
	v_pk_mul_f32 v[62:63], v[66:67], v[64:65]
	s_waitcnt lgkmcnt(0)
	v_mov_b32_e32 v92, v84
	v_mov_b32_e32 v93, v86
	v_mov_b32_e32 v86, v85
	v_pk_mul_f32 v[66:67], v[66:67], v[90:91]
	v_pk_fma_f32 v[62:63], v[50:51], v[90:91], v[62:63] neg_lo:[0,0,1] neg_hi:[0,0,1]
	v_pk_mul_f32 v[84:85], v[68:69], v[86:87]
	v_pk_fma_f32 v[50:51], v[50:51], v[64:65], v[66:67]
	v_pk_mul_f32 v[64:65], v[68:69], v[92:93]
	v_pk_fma_f32 v[84:85], v[52:53], v[92:93], v[84:85] neg_lo:[0,0,1] neg_hi:[0,0,1]
	v_pk_fma_f32 v[52:53], v[52:53], v[86:87], v[64:65]
	v_cvt_pk_bf16_f32 v62, v62, v63
	v_cvt_pk_bf16_f32 v63, v84, v85
	v_cvt_pk_bf16_f32 v50, v50, v51
	v_cvt_pk_bf16_f32 v51, v52, v53
	v_add_u32_e32 v52, v88, v71
	ds_write_b64 v52, v[62:63]
	v_add_u32_e32 v52, v88, v100
	ds_write_b64 v52, v[50:51]
	ds_read_b128 v[50:53], v75 offset:128
	ds_read_b128 v[62:65], v75 offset:144
	s_waitcnt lgkmcnt(1)
	v_mov_b32_e32 v66, v50
	v_mov_b32_e32 v67, v52
	v_mov_b32_e32 v52, v51
	v_pk_mul_f32 v[50:51], v[58:59], v[52:53]
	s_waitcnt lgkmcnt(0)
	v_mov_b32_e32 v68, v62
	v_mov_b32_e32 v69, v64
	v_mov_b32_e32 v64, v63
	v_pk_mul_f32 v[58:59], v[58:59], v[66:67]
	v_pk_fma_f32 v[50:51], v[42:43], v[66:67], v[50:51] neg_lo:[0,0,1] neg_hi:[0,0,1]
	v_pk_mul_f32 v[62:63], v[60:61], v[64:65]
	v_pk_fma_f32 v[42:43], v[42:43], v[52:53], v[58:59]
	v_pk_mul_f32 v[52:53], v[60:61], v[68:69]
	v_pk_fma_f32 v[62:63], v[44:45], v[68:69], v[62:63] neg_lo:[0,0,1] neg_hi:[0,0,1]
	v_pk_fma_f32 v[44:45], v[44:45], v[64:65], v[52:53]
	v_cvt_pk_bf16_f32 v50, v50, v51
	v_cvt_pk_bf16_f32 v51, v62, v63
	v_cvt_pk_bf16_f32 v42, v42, v43
	v_cvt_pk_bf16_f32 v43, v44, v45
	v_add_u32_e32 v44, v88, v83
	ds_write_b64 v44, v[50:51]
	v_add_u32_e32 v44, v88, v94
	ds_write_b64 v44, v[42:43]
	v_add_u32_e32 v62, v77, v74
	ds_read_b128 v[42:45], v62
	ds_read_b128 v[50:53], v62 offset:16
	v_add_u32_e32 v63, 0x9000, v70
	s_waitcnt lgkmcnt(1)
	v_mov_b32_e32 v59, v44
	v_mov_b32_e32 v44, v43
	s_waitcnt lgkmcnt(0)
	v_mov_b32_e32 v61, v52
	v_mov_b32_e32 v52, v51
	v_mov_b32_e32 v58, v42
	v_pk_mul_f32 v[42:43], v[54:55], v[44:45]
	v_mov_b32_e32 v60, v50
	v_pk_mul_f32 v[50:51], v[56:57], v[52:53]
	v_pk_fma_f32 v[42:43], v[34:35], v[58:59], v[42:43] neg_lo:[0,0,1] neg_hi:[0,0,1]
	v_pk_fma_f32 v[50:51], v[36:37], v[60:61], v[50:51] neg_lo:[0,0,1] neg_hi:[0,0,1]
	v_cvt_pk_bf16_f32 v42, v42, v43
	v_cvt_pk_bf16_f32 v43, v50, v51
	v_pk_mul_f32 v[50:51], v[54:55], v[58:59]
	s_nop 0
	v_pk_fma_f32 v[34:35], v[34:35], v[44:45], v[50:51]
	v_pk_mul_f32 v[44:45], v[56:57], v[60:61]
	v_cvt_pk_bf16_f32 v34, v34, v35
	v_pk_fma_f32 v[36:37], v[36:37], v[52:53], v[44:45]
	s_nop 0
	v_cvt_pk_bf16_f32 v35, v36, v37
	v_add_u32_e32 v36, v63, v71
	ds_write_b64 v36, v[42:43]
	v_add_u32_e32 v36, v63, v100
	ds_write_b64 v36, v[34:35]
	ds_read_b128 v[34:37], v62 offset:128
	ds_read_b128 v[42:45], v62 offset:144
	s_waitcnt lgkmcnt(1)
	v_mov_b32_e32 v51, v36
	v_mov_b32_e32 v36, v35
	s_waitcnt lgkmcnt(0)
	v_mov_b32_e32 v53, v44
	v_mov_b32_e32 v44, v43
	v_mov_b32_e32 v50, v34
	v_pk_mul_f32 v[34:35], v[46:47], v[36:37]
	v_mov_b32_e32 v52, v42
	v_pk_mul_f32 v[42:43], v[48:49], v[44:45]
	v_pk_fma_f32 v[34:35], v[26:27], v[50:51], v[34:35] neg_lo:[0,0,1] neg_hi:[0,0,1]
	v_pk_fma_f32 v[42:43], v[28:29], v[52:53], v[42:43] neg_lo:[0,0,1] neg_hi:[0,0,1]
	v_cvt_pk_bf16_f32 v34, v34, v35
	v_cvt_pk_bf16_f32 v35, v42, v43
	v_pk_mul_f32 v[42:43], v[46:47], v[50:51]
	v_add_u32_e32 v46, v77, v73
	v_pk_fma_f32 v[26:27], v[26:27], v[36:37], v[42:43]
	v_pk_mul_f32 v[36:37], v[48:49], v[52:53]
	v_cvt_pk_bf16_f32 v26, v26, v27
	v_pk_fma_f32 v[28:29], v[28:29], v[44:45], v[36:37]
	v_add_u32_e32 v47, 0xd800, v70
	v_cvt_pk_bf16_f32 v27, v28, v29
	v_add_u32_e32 v28, v63, v83
	ds_write_b64 v28, v[34:35]
	v_add_u32_e32 v28, v63, v94
	ds_write_b64 v28, v[26:27]
	ds_read_b128 v[26:29], v46
	ds_read_b128 v[34:37], v46 offset:16
	s_waitcnt lgkmcnt(1)
	v_mov_b32_e32 v43, v28
	v_mov_b32_e32 v28, v27
	s_waitcnt lgkmcnt(0)
	v_mov_b32_e32 v45, v36
	v_mov_b32_e32 v36, v35
	v_mov_b32_e32 v42, v26
	v_pk_mul_f32 v[26:27], v[38:39], v[28:29]
	v_mov_b32_e32 v44, v34
	v_pk_mul_f32 v[34:35], v[40:41], v[36:37]
	v_pk_fma_f32 v[26:27], v[22:23], v[42:43], v[26:27] neg_lo:[0,0,1] neg_hi:[0,0,1]
	v_pk_fma_f32 v[34:35], v[24:25], v[44:45], v[34:35] neg_lo:[0,0,1] neg_hi:[0,0,1]
	v_cvt_pk_bf16_f32 v26, v26, v27
	v_cvt_pk_bf16_f32 v27, v34, v35
	v_pk_mul_f32 v[34:35], v[38:39], v[42:43]
	s_nop 0
	v_pk_fma_f32 v[22:23], v[22:23], v[28:29], v[34:35]
	v_pk_mul_f32 v[28:29], v[40:41], v[44:45]
	v_cvt_pk_bf16_f32 v22, v22, v23
	v_pk_fma_f32 v[24:25], v[24:25], v[36:37], v[28:29]
	s_nop 0
	v_cvt_pk_bf16_f32 v23, v24, v25
	v_add_u32_e32 v24, v47, v71
	ds_write_b64 v24, v[26:27]
	v_add_u32_e32 v24, v47, v100
	ds_write_b64 v24, v[22:23]
	ds_read_b128 v[22:25], v46 offset:128
	ds_read_b128 v[26:29], v46 offset:144
	v_lshlrev_b32_e32 v46, 2, v82
	v_or_b32_e32 v42, 2, v46
	s_waitcnt lgkmcnt(1)
	v_mov_b32_e32 v35, v24
	v_mov_b32_e32 v24, v23
	s_waitcnt lgkmcnt(0)
	v_mov_b32_e32 v37, v28
	v_mov_b32_e32 v28, v27
	v_mov_b32_e32 v34, v22
	v_pk_mul_f32 v[22:23], v[30:31], v[24:25]
	v_mov_b32_e32 v36, v26
	v_pk_mul_f32 v[26:27], v[32:33], v[28:29]
	v_pk_fma_f32 v[22:23], v[18:19], v[34:35], v[22:23] neg_lo:[0,0,1] neg_hi:[0,0,1]
	v_pk_fma_f32 v[26:27], v[20:21], v[36:37], v[26:27] neg_lo:[0,0,1] neg_hi:[0,0,1]
	v_cvt_pk_bf16_f32 v22, v22, v23
	v_cvt_pk_bf16_f32 v23, v26, v27
	v_pk_mul_f32 v[26:27], v[30:31], v[34:35]
	s_nop 0
	v_pk_fma_f32 v[18:19], v[18:19], v[24:25], v[26:27]
	v_pk_mul_f32 v[24:25], v[32:33], v[36:37]
	v_cvt_pk_bf16_f32 v18, v18, v19
	v_pk_fma_f32 v[20:21], v[20:21], v[28:29], v[24:25]
	v_bitop3_b32 v27, v81, v46, 4 bitop3:0x72
	v_cvt_pk_bf16_f32 v19, v20, v21
	v_add_u32_e32 v20, v47, v83
	ds_write_b64 v20, v[22:23]
	v_add_u32_e32 v20, v47, v94
	ds_write_b64 v20, v[18:19]
	v_and_b32_e32 v18, 0xfffffcf, v78
	v_mul_lo_u32 v18, v18, s10
	v_add_u32_e32 v26, 0, v18
	v_and_or_b32 v18, v46, 4, v81
	v_lshl_add_u32 v18, v18, 4, v26
	s_waitcnt lgkmcnt(0)
	s_barrier
	ds_read_b128 v[18:21], v18
	v_lshl_add_u32 v26, v27, 4, v26
	ds_read_b128 v[26:29], v26
	s_waitcnt vmcnt(3) lgkmcnt(1)
	v_mfma_f32_16x16x32_bf16 v[22:25], v[18:21], v[10:13], 0
	v_or_b32_e32 v47, 4, v81
	s_waitcnt vmcnt(1)
	v_mfma_f32_16x16x32_bf16 v[18:21], v[18:21], v[14:17], 0
	s_waitcnt lgkmcnt(0)
	v_mfma_f32_16x16x32_bf16 v[38:41], v[26:29], v[6:9], v[22:25]
	s_waitcnt vmcnt(0)
	v_mfma_f32_16x16x32_bf16 v[34:37], v[26:29], v[2:5], v[18:21]
	v_or_b32_e32 v26, 1, v46
	v_or_b32_e32 v46, 3, v46
	s_nop 1
	v_lshl_or_b32 v18, v26, 4, v80
	v_mul_lo_u32 v18, v18, s10
	v_add_u32_e32 v27, 0, v18
	v_bitop3_b32 v18, v26, v81, 5 bitop3:0x6c
	v_lshl_add_u32 v18, v18, 4, v27
	ds_read_b128 v[18:21], v18
	v_bitop3_b32 v26, v26, v47, 5 bitop3:0x6c
	v_lshl_add_u32 v26, v26, 4, v27
	ds_read_b128 v[26:29], v26
	s_waitcnt lgkmcnt(1)
	v_mfma_f32_16x16x32_bf16 v[22:25], v[18:21], v[10:13], 0
	v_mfma_f32_16x16x32_bf16 v[18:21], v[18:21], v[14:17], 0
	s_waitcnt lgkmcnt(0)
	v_mfma_f32_16x16x32_bf16 v[30:33], v[26:29], v[6:9], v[22:25]
	v_mfma_f32_16x16x32_bf16 v[26:29], v[26:29], v[2:5], v[18:21]
	s_nop 4
	v_lshl_or_b32 v18, v42, 4, v80
	v_mul_lo_u32 v18, v18, s10
	v_add_u32_e32 v43, 0, v18
	v_bitop3_b32 v18, v42, v81, 6 bitop3:0x6c
	v_lshl_add_u32 v18, v18, 4, v43
	ds_read_b128 v[18:21], v18
	v_bitop3_b32 v42, v42, v47, 6 bitop3:0x6c
	v_lshl_add_u32 v42, v42, 4, v43
	ds_read_b128 v[42:45], v42
	s_waitcnt lgkmcnt(1)
	v_mfma_f32_16x16x32_bf16 v[22:25], v[18:21], v[10:13], 0
	v_mfma_f32_16x16x32_bf16 v[18:21], v[18:21], v[14:17], 0
	s_waitcnt lgkmcnt(0)
	v_mfma_f32_16x16x32_bf16 v[22:25], v[42:45], v[6:9], v[22:25]
	v_mfma_f32_16x16x32_bf16 v[18:21], v[42:45], v[2:5], v[18:21]
	v_lshl_or_b32 v42, v46, 4, v80
	v_mul_lo_u32 v42, v42, s10
	v_add_u32_e32 v48, 0, v42
	v_bitop3_b32 v42, v46, v81, 7 bitop3:0x6c
	v_lshl_add_u32 v42, v42, 4, v48
	ds_read_b128 v[42:45], v42
	s_waitcnt lgkmcnt(0)
	v_mfma_f32_16x16x32_bf16 v[10:13], v[42:45], v[10:13], 0
	v_mfma_f32_16x16x32_bf16 v[14:17], v[42:45], v[14:17], 0
	v_bitop3_b32 v42, v46, v47, 7 bitop3:0x6c
	v_lshl_add_u32 v42, v42, 4, v48
	ds_read_b128 v[42:45], v42
	s_waitcnt lgkmcnt(0)
	v_mfma_f32_16x16x32_bf16 v[6:9], v[42:45], v[6:9], v[10:13]
	s_nop 2
	v_and_b32_e32 v13, 64, v1
	v_lshlrev_b32_e32 v10, 3, v82
	v_xor_b32_e32 v11, 16, v1
	v_add_u32_e32 v13, 64, v13
	v_add3_u32 v10, v10, s1, v79
	v_cmp_lt_i32_e32 vcc, v11, v13
	v_or_b32_e32 v10, v10, v76
	v_mfma_f32_16x16x32_bf16 v[2:5], v[42:45], v[2:5], v[14:17]
	v_cndmask_b32_e32 v11, v1, v11, vcc
	s_lshl_b32 s1, s7, 2
	v_bfe_u32 v12, v78, 4, 1
	v_lshlrev_b32_e32 v14, 2, v11
	v_pk_mul_f32 v[16:17], v[38:39], s[88:89] op_sel_hi:[1,0]
	v_pk_mul_f32 v[38:39], v[40:41], s[88:89] op_sel_hi:[1,0]
	v_ashrrev_i32_e32 v11, 31, v10
	v_cvt_pk_bf16_f32 v16, v16, v17
	v_cvt_pk_bf16_f32 v17, v38, v39
	v_lshlrev_b64 v[38:39], 11, v[10:11]
	s_add_u32 s22, s24, s1
	v_lshl_add_u64 v[38:39], s[84:85], 0, v[38:39]
	s_mov_b32 s1, s69
	v_lshl_add_u64 v[38:39], v[38:39], 0, s[0:1]
	v_lshlrev_b32_e32 v98, 3, v12
	v_lshl_add_u64 v[38:39], v[38:39], 0, v[98:99]
	s_mov_b32 s0, 0x1b00000
	v_add_co_u32_e32 v38, vcc, s0, v38
	v_and_b32_e32 v15, 0xffff0000, v16
	s_nop 0
	v_addc_co_u32_e32 v39, vcc, 0, v39, vcc
	global_store_dwordx2 v[38:39], v[16:17], off offset:1024
	v_lshlrev_b32_e32 v13, 16, v16
	v_mul_f32_e32 v15, v15, v15
	v_and_b32_e32 v16, 0xffff0000, v17
	v_fmac_f32_e32 v15, v13, v13
	v_lshlrev_b32_e32 v13, 16, v17
	v_mul_f32_e32 v16, v16, v16
	v_fmac_f32_e32 v16, v13, v13
	v_add_f32_e32 v13, v15, v16
	v_mov_b32_e32 v15, v13
	s_nop 1
	v_permlane16_swap_b32_e32 v13, v15
	v_cmp_eq_u32_e64 s[38:39], 0, v12
	s_addc_u32 s23, s25, 0
	s_and_saveexec_b64 s[0:1], s[38:39]
	s_cbranch_execz .LBB0_805
	v_lshlrev_b64 v[16:17], 7, v[10:11]
	s_waitcnt lgkmcnt(0)
	v_add_f32_e32 v13, v13, v15
	v_lshl_add_u64 v[16:17], s[22:23], 0, v[16:17]
	global_store_dword v[16:17], v13, off

.LBB0_1250:
	global_load_dwordx4 v[134:137], v[20:21], off
	global_load_dwordx4 v[138:141], v[22:23], off
	global_load_dwordx4 v[142:145], v[16:17], off offset:1024
	global_load_dwordx4 v[146:149], v[24:25], off
	global_load_dwordx4 v[150:153], v[26:27], off
	global_load_dwordx4 v[154:157], v[16:17], off offset:2048
	global_load_dwordx4 v[158:161], v[28:29], off
	global_load_dwordx4 v[162:165], v[16:17], off offset:3072
	global_load_dwordx4 v[166:169], v[30:31], off
	v_add_co_u32_e32 v40, vcc, 0x400000, v38
	global_load_dwordx2 v[50:51], v[38:39], off nt
	s_nop 0
	v_addc_co_u32_e32 v41, vcc, 0, v39, vcc
	v_add_co_u32_e32 v42, vcc, 0x800000, v38
	global_load_dwordx2 v[52:53], v[40:41], off nt
	s_nop 0
	v_addc_co_u32_e32 v43, vcc, 0, v39, vcc
	global_load_dwordx2 v[92:93], v[42:43], off nt
	v_add_co_u32_e32 v48, vcc, 0xc00000, v38
	global_load_dwordx4 v[76:79], v[18:19], off
	s_nop 0
	v_addc_co_u32_e32 v49, vcc, 0, v39, vcc
	global_load_dwordx2 v[94:95], v[48:49], off nt
	global_load_dwordx4 v[80:83], v[36:37], off nt
	global_load_dwordx4 v[84:87], v[14:15], off
	global_load_dwordx4 v[88:91], v[16:17], off
	s_add_i32 s0, s2, 0x4000
	global_load_dwordx4 v[10:13], v[36:37], off offset:1024 nt
	global_load_dwordx4 v[6:9], v[36:37], off offset:2048 nt
	s_waitcnt lgkmcnt(0)
	global_load_dwordx4 v[2:5], v[36:37], off offset:3072 nt
	global_load_dwordx2 v[66:67], v[38:39], off offset:512 nt
	global_load_dwordx2 v[58:59], v[38:39], off offset:1024 nt
	global_load_dwordx2 v[46:47], v[38:39], off offset:1536 nt
	s_ashr_i32 s1, s0, 31
	s_lshl_b64 s[22:23], s[0:1], 11
	global_load_dwordx2 v[64:65], v[40:41], off offset:512 nt
	global_load_dwordx2 v[56:57], v[40:41], off offset:1024 nt
	global_load_dwordx2 v[44:45], v[40:41], off offset:1536 nt
	global_load_dwordx2 v[62:63], v[42:43], off offset:512 nt
	global_load_dwordx2 v[54:55], v[42:43], off offset:1024 nt
	s_nop 0
	global_load_dwordx2 v[42:43], v[42:43], off offset:1536 nt
	v_lshl_add_u64 v[40:41], v[34:35], 0, s[22:23]
	global_load_dwordx2 v[68:69], v[48:49], off offset:512 nt
	global_load_dwordx2 v[60:61], v[48:49], off offset:1024 nt
	s_nop 0
	global_load_dwordx2 v[48:49], v[48:49], off offset:1536 nt
	s_waitcnt vmcnt(0)
	v_lshlrev_b32_e32 v96, 16, v50
	v_and_b32_e32 v97, 0xffff0000, v50
	v_lshlrev_b32_e32 v50, 16, v51
	v_and_b32_e32 v51, 0xffff0000, v51
	v_pk_add_f32 v[96:97], v[96:97], 0 op_sel_hi:[1,0]
	v_pk_add_f32 v[50:51], v[50:51], 0 op_sel_hi:[1,0]
	v_lshlrev_b32_e32 v100, 16, v52
	v_and_b32_e32 v101, 0xffff0000, v52
	v_lshlrev_b32_e32 v52, 16, v53
	v_and_b32_e32 v53, 0xffff0000, v53
	v_pk_add_f32 v[96:97], v[96:97], v[100:101]
	v_lshlrev_b32_e32 v100, 16, v92
	v_and_b32_e32 v101, 0xffff0000, v92
	v_pk_add_f32 v[50:51], v[50:51], v[52:53]
	v_lshlrev_b32_e32 v52, 16, v93
	v_and_b32_e32 v53, 0xffff0000, v93
	v_pk_add_f32 v[92:93], v[96:97], v[100:101]
	v_lshlrev_b32_e32 v96, 16, v94
	v_and_b32_e32 v97, 0xffff0000, v94
	v_pk_add_f32 v[50:51], v[50:51], v[52:53]
	v_lshlrev_b32_e32 v52, 16, v95
	v_and_b32_e32 v53, 0xffff0000, v95
	v_pk_add_f32 v[92:93], v[92:93], v[96:97]
	v_pk_add_f32 v[50:51], v[50:51], v[52:53]
	v_pk_fma_f32 v[52:53], v[92:93], v[84:85], v[80:81]
	v_pk_fma_f32 v[50:51], v[50:51], v[86:87], v[82:83]
	v_pk_add_f32 v[78:79], v[78:79], 1.0 op_sel_hi:[1,0]
	v_pk_add_f32 v[76:77], v[76:77], 1.0 op_sel_hi:[1,0]
	v_pk_mul_f32 v[80:81], v[88:89], v[52:53]
	v_pk_mul_f32 v[82:83], v[90:91], v[50:51]
	v_pk_mul_f32 v[76:77], v[80:81], v[76:77]
	v_pk_mul_f32 v[78:79], v[82:83], v[78:79]
	v_cvt_pk_bf16_f32 v76, v76, v77
	v_cvt_pk_bf16_f32 v77, v78, v79
	global_store_dwordx2 v[40:41], v[76:77], off
	v_mov_b32_e32 v76, v134
	v_mov_b32_e32 v77, v135
	v_mov_b32_e32 v78, v136
	v_mov_b32_e32 v79, v137
	s_nop 0
	v_mov_b32_e32 v80, v138
	v_mov_b32_e32 v81, v139
	v_mov_b32_e32 v82, v140
	v_mov_b32_e32 v83, v141
	v_mov_b32_e32 v84, v142
	v_mov_b32_e32 v85, v143
	v_mov_b32_e32 v86, v144
	v_mov_b32_e32 v87, v145
	v_lshlrev_b32_e32 v88, 16, v66
	v_and_b32_e32 v89, 0xffff0000, v66
	v_lshlrev_b32_e32 v66, 16, v67
	v_and_b32_e32 v67, 0xffff0000, v67
	v_pk_add_f32 v[88:89], v[88:89], 0 op_sel_hi:[1,0]
	v_pk_add_f32 v[66:67], v[66:67], 0 op_sel_hi:[1,0]
	v_lshlrev_b32_e32 v90, 16, v64
	v_and_b32_e32 v91, 0xffff0000, v64
	v_lshlrev_b32_e32 v64, 16, v65
	v_and_b32_e32 v65, 0xffff0000, v65
	v_pk_add_f32 v[88:89], v[88:89], v[90:91]
	v_lshlrev_b32_e32 v90, 16, v62
	v_and_b32_e32 v91, 0xffff0000, v62
	v_pk_add_f32 v[64:65], v[66:67], v[64:65]
	v_lshlrev_b32_e32 v62, 16, v63
	v_and_b32_e32 v63, 0xffff0000, v63
	v_pk_add_f32 v[66:67], v[88:89], v[90:91]
	v_lshlrev_b32_e32 v88, 16, v68
	v_and_b32_e32 v89, 0xffff0000, v68
	v_pk_add_f32 v[62:63], v[64:65], v[62:63]
	v_lshlrev_b32_e32 v64, 16, v69
	v_and_b32_e32 v65, 0xffff0000, v69
	v_pk_add_f32 v[66:67], v[66:67], v[88:89]
	v_pk_add_f32 v[62:63], v[62:63], v[64:65]
	v_pk_fma_f32 v[10:11], v[66:67], v[76:77], v[10:11]
	v_pk_fma_f32 v[12:13], v[62:63], v[78:79], v[12:13]
	v_pk_add_f32 v[62:63], v[82:83], 1.0 op_sel_hi:[1,0]
	v_pk_add_f32 v[64:65], v[80:81], 1.0 op_sel_hi:[1,0]
	v_pk_mul_f32 v[66:67], v[84:85], v[10:11]
	v_pk_mul_f32 v[68:69], v[86:87], v[12:13]
	v_pk_mul_f32 v[64:65], v[66:67], v[64:65]
	v_pk_mul_f32 v[62:63], v[68:69], v[62:63]
	v_cvt_pk_bf16_f32 v64, v64, v65
	v_cvt_pk_bf16_f32 v65, v62, v63
	global_store_dwordx2 v[40:41], v[64:65], off offset:512
	v_mov_b32_e32 v62, v146
	v_mov_b32_e32 v63, v147
	v_mov_b32_e32 v64, v148
	v_mov_b32_e32 v65, v149
	s_nop 0
	v_mov_b32_e32 v66, v150
	v_mov_b32_e32 v67, v151
	v_mov_b32_e32 v68, v152
	v_mov_b32_e32 v69, v153
	v_mov_b32_e32 v76, v154
	v_mov_b32_e32 v77, v155
	v_mov_b32_e32 v78, v156
	v_mov_b32_e32 v79, v157
	v_lshlrev_b32_e32 v80, 16, v58
	v_and_b32_e32 v81, 0xffff0000, v58
	v_lshlrev_b32_e32 v58, 16, v59
	v_and_b32_e32 v59, 0xffff0000, v59
	v_pk_add_f32 v[80:81], v[80:81], 0 op_sel_hi:[1,0]
	v_pk_add_f32 v[58:59], v[58:59], 0 op_sel_hi:[1,0]
	v_lshlrev_b32_e32 v82, 16, v56
	v_and_b32_e32 v83, 0xffff0000, v56
	v_lshlrev_b32_e32 v56, 16, v57
	v_and_b32_e32 v57, 0xffff0000, v57
	v_pk_add_f32 v[80:81], v[80:81], v[82:83]
	v_lshlrev_b32_e32 v82, 16, v54
	v_and_b32_e32 v83, 0xffff0000, v54
	v_pk_add_f32 v[56:57], v[58:59], v[56:57]
	v_lshlrev_b32_e32 v54, 16, v55
	v_and_b32_e32 v55, 0xffff0000, v55
	v_pk_add_f32 v[58:59], v[80:81], v[82:83]
	v_lshlrev_b32_e32 v80, 16, v60
	v_and_b32_e32 v81, 0xffff0000, v60
	v_pk_add_f32 v[54:55], v[56:57], v[54:55]
	v_lshlrev_b32_e32 v56, 16, v61
	v_and_b32_e32 v57, 0xffff0000, v61
	v_pk_add_f32 v[58:59], v[58:59], v[80:81]
	v_pk_add_f32 v[54:55], v[54:55], v[56:57]
	v_mul_f32_e32 v11, v11, v11
	v_mul_f32_e32 v13, v13, v13
	v_fmac_f32_e32 v11, v10, v10
	v_fmac_f32_e32 v13, v12, v12
	v_add_f32_e32 v10, v11, v13
	v_pk_fma_f32 v[54:55], v[54:55], v[64:65], v[8:9]
	v_pk_fma_f32 v[56:57], v[58:59], v[62:63], v[6:7]
	v_pk_add_f32 v[6:7], v[68:69], 1.0 op_sel_hi:[1,0]
	v_pk_add_f32 v[8:9], v[66:67], 1.0 op_sel_hi:[1,0]
	v_pk_mul_f32 v[58:59], v[76:77], v[56:57]
	v_pk_mul_f32 v[60:61], v[78:79], v[54:55]
	v_pk_mul_f32 v[8:9], v[58:59], v[8:9]
	v_pk_mul_f32 v[6:7], v[60:61], v[6:7]
	v_cvt_pk_bf16_f32 v8, v8, v9
	v_cvt_pk_bf16_f32 v9, v6, v7
	global_store_dwordx2 v[40:41], v[8:9], off offset:1024
	v_mov_b32_e32 v58, v158
	v_mov_b32_e32 v59, v159
	v_mov_b32_e32 v60, v160
	v_mov_b32_e32 v61, v161
	s_nop 0
	v_mov_b32_e32 v6, v162
	v_mov_b32_e32 v7, v163
	v_mov_b32_e32 v8, v164
	v_mov_b32_e32 v9, v165
	v_mov_b32_e32 v62, v166
	v_mov_b32_e32 v63, v167
	v_mov_b32_e32 v64, v168
	v_mov_b32_e32 v65, v169
	v_lshlrev_b32_e32 v66, 16, v46
	v_and_b32_e32 v67, 0xffff0000, v46
	v_lshlrev_b32_e32 v46, 16, v47
	v_and_b32_e32 v47, 0xffff0000, v47
	v_pk_add_f32 v[66:67], v[66:67], 0 op_sel_hi:[1,0]
	v_pk_add_f32 v[46:47], v[46:47], 0 op_sel_hi:[1,0]
	v_lshlrev_b32_e32 v68, 16, v44
	v_and_b32_e32 v69, 0xffff0000, v44
	v_lshlrev_b32_e32 v44, 16, v45
	v_and_b32_e32 v45, 0xffff0000, v45
	v_pk_add_f32 v[66:67], v[66:67], v[68:69]
	v_lshlrev_b32_e32 v68, 16, v42
	v_and_b32_e32 v69, 0xffff0000, v42
	v_pk_add_f32 v[44:45], v[46:47], v[44:45]
	v_lshlrev_b32_e32 v42, 16, v43
	v_and_b32_e32 v43, 0xffff0000, v43
	v_pk_add_f32 v[42:43], v[44:45], v[42:43]
	v_lshlrev_b32_e32 v44, 16, v49
	v_and_b32_e32 v45, 0xffff0000, v49
	v_pk_add_f32 v[42:43], v[42:43], v[44:45]
	v_mul_f32_e32 v44, v53, v53
	v_mul_f32_e32 v45, v51, v51
	v_pk_add_f32 v[46:47], v[66:67], v[68:69]
	v_lshlrev_b32_e32 v66, 16, v48
	v_and_b32_e32 v67, 0xffff0000, v48
	v_fmac_f32_e32 v44, v52, v52
	v_fmac_f32_e32 v45, v50, v50
	v_mul_f32_e32 v11, v57, v57
	v_mul_f32_e32 v12, v55, v55
	v_pk_add_f32 v[46:47], v[46:47], v[66:67]
	v_add_f32_e32 v44, v44, v45
	v_fmac_f32_e32 v11, v56, v56
	v_fmac_f32_e32 v12, v54, v54
	v_add_f32_e32 v10, v44, v10
	v_add_f32_e32 v11, v11, v12
	v_add_f32_e32 v10, v10, v11
	v_pk_fma_f32 v[4:5], v[42:43], v[60:61], v[4:5]
	v_pk_fma_f32 v[2:3], v[46:47], v[58:59], v[2:3]
	v_mul_f32_e32 v12, v5, v5
	v_mul_f32_e32 v11, v3, v3
	v_fmac_f32_e32 v11, v2, v2
	v_fmac_f32_e32 v12, v4, v4
	v_add_f32_e32 v11, v11, v12
	v_add_f32_e32 v10, v10, v11
	s_nop 1
	v_mov_b32_dpp v11, v10 quad_perm:[1,0,3,2] row_mask:0xf bank_mask:0xf
	v_pk_mul_f32 v[6:7], v[6:7], v[2:3]
	v_pk_mul_f32 v[2:3], v[8:9], v[4:5]
	v_pk_add_f32 v[4:5], v[64:65], 1.0 op_sel_hi:[1,0]
	v_pk_add_f32 v[8:9], v[62:63], 1.0 op_sel_hi:[1,0]
	s_waitcnt lgkmcnt(0)
	v_add_f32_e32 v10, v10, v11
	s_nop 1
	v_mov_b32_dpp v11, v10 quad_perm:[2,3,0,1] row_mask:0xf bank_mask:0xf
	v_pk_mul_f32 v[4:5], v[2:3], v[4:5]
	v_pk_mul_f32 v[6:7], v[6:7], v[8:9]
	s_waitcnt lgkmcnt(0)
	v_add_f32_e32 v10, v10, v11
	s_nop 1
	v_mov_b32_dpp v11, v10 row_half_mirror row_mask:0xf bank_mask:0xf
	v_cvt_pk_bf16_f32 v6, v6, v7
	v_cvt_pk_bf16_f32 v7, v4, v5
	global_store_dwordx2 v[40:41], v[6:7], off offset:1536
	s_waitcnt lgkmcnt(0)
	v_add_f32_e32 v10, v10, v11
	s_nop 1
	v_mov_b32_dpp v11, v10 row_mirror row_mask:0xf bank_mask:0xf
	s_waitcnt lgkmcnt(0)
	v_add_f32_e32 v10, v10, v11
	v_mov_b32_e32 v11, v10
	s_nop 1
	v_permlane16_swap_b32_e32 v10, v11
	s_waitcnt lgkmcnt(0)
	v_add_f32_e32 v2, v10, v11
	v_mov_b32_e32 v3, v2
	s_nop 1
	v_permlane32_swap_b32_e32 v2, v3
	s_and_saveexec_b64 s[22:23], s[38:39]
	s_cbranch_execz .LBB0_1249
	s_lshl_b64 s[0:1], s[0:1], 6
	s_waitcnt lgkmcnt(0)
	v_add_f32_e32 v2, v2, v3
	v_lshl_add_u64 v[4:5], v[32:33], 0, s[0:1]
	v_cndmask_b32_e64 v2, 0, v2, s[40:41]
	global_store_dword v[4:5], v2, off
	s_branch .LBB0_1249

.LBB0_1638:
	s_waitcnt lgkmcnt(0)
	global_load_dwordx4 v[134:137], v[6:7], off
	global_load_dwordx4 v[138:141], v[8:9], off
	global_load_dwordx4 v[142:145], v[10:11], off
	global_load_dwordx4 v[146:149], v[12:13], off
	global_load_dwordx4 v[150:153], v[14:15], off
	global_load_dwordx4 v[154:157], v[6:7], off offset:1024
	global_load_dwordx4 v[158:161], v[16:17], off
	global_load_dwordx4 v[162:165], v[18:19], off
	global_load_dwordx4 v[166:169], v[20:21], off
	global_load_dwordx4 v[170:173], v[22:23], off
	global_load_dwordx4 v[174:177], v[6:7], off offset:2048
	global_load_dwordx4 v[178:181], v[24:25], off
	global_load_dwordx4 v[182:185], v[26:27], off
	global_load_dwordx4 v[186:189], v[28:29], off
	global_load_dwordx4 v[190:193], v[30:31], off
	global_load_dwordx4 v[194:197], v[6:7], off offset:3072
	global_load_dwordx4 v[204:207], v[32:33], off
	global_load_dwordx4 v[208:211], v[34:35], off
	global_load_dwordx4 v[214:217], v[36:37], off
	global_load_dwordx4 v[218:221], v[38:39], off
	v_lshl_add_u64 v[2:3], s[86:87], 0, v[42:43]
	v_add_co_u32_e32 v46, vcc, 0x4d00000, v2
	v_lshl_add_u64 v[4:5], s[86:87], 0, v[40:41]
	s_nop 0
	v_addc_co_u32_e32 v47, vcc, 0, v3, vcc
	global_load_dwordx2 v[2:3], v[46:47], off
	v_add_co_u32_e32 v48, vcc, 0xd400000, v4
	s_nop 1
	v_addc_co_u32_e32 v49, vcc, 0, v5, vcc
	v_add_co_u32_e32 v50, vcc, 0xd800000, v4
	global_load_dwordx2 v[104:105], v[48:49], off nt
	s_nop 0
	v_addc_co_u32_e32 v51, vcc, 0, v5, vcc
	v_add_co_u32_e32 v52, vcc, 0xdc00000, v4
	global_load_dwordx2 v[106:107], v[50:51], off nt
	s_nop 0
	v_addc_co_u32_e32 v53, vcc, 0, v5, vcc
	v_add_co_u32_e32 v54, vcc, 0xe000000, v4
	global_load_dwordx2 v[108:109], v[52:53], off nt
	s_nop 0
	v_addc_co_u32_e32 v55, vcc, 0, v5, vcc
	v_add_co_u32_e32 v126, vcc, 0xe400000, v4
	global_load_dwordx2 v[110:111], v[54:55], off nt
	s_nop 0
	v_addc_co_u32_e32 v127, vcc, 0, v5, vcc
	v_add_co_u32_e32 v128, vcc, 0xe800000, v4
	global_load_dwordx2 v[112:113], v[126:127], off nt
	s_nop 0
	v_addc_co_u32_e32 v129, vcc, 0, v5, vcc
	v_add_co_u32_e32 v130, vcc, 0xec00000, v4
	global_load_dwordx2 v[114:115], v[128:129], off nt
	s_nop 0
	v_addc_co_u32_e32 v131, vcc, 0, v5, vcc
	v_add_co_u32_e32 v4, vcc, 0xf000000, v4
	global_load_dwordx2 v[116:117], v[130:131], off nt
	s_nop 0
	v_addc_co_u32_e32 v5, vcc, 0, v5, vcc
	global_load_dwordx2 v[118:119], v[4:5], off nt
	global_load_dwordx2 v[102:103], v[46:47], off offset:512
	global_load_dwordx2 v[100:101], v[48:49], off offset:512 nt
	global_load_dwordx2 v[96:97], v[50:51], off offset:512 nt
	global_load_dwordx2 v[94:95], v[52:53], off offset:512 nt
	global_load_dwordx2 v[92:93], v[54:55], off offset:512 nt
	global_load_dwordx2 v[90:91], v[126:127], off offset:512 nt
	global_load_dwordx2 v[88:89], v[128:129], off offset:512 nt
	global_load_dwordx2 v[86:87], v[130:131], off offset:512 nt
	global_load_dwordx2 v[84:85], v[4:5], off offset:512 nt
	global_load_dwordx2 v[82:83], v[46:47], off offset:1024
	global_load_dwordx2 v[80:81], v[48:49], off offset:1024 nt
	global_load_dwordx2 v[78:79], v[50:51], off offset:1024 nt
	global_load_dwordx2 v[76:77], v[52:53], off offset:1024 nt
	global_load_dwordx2 v[74:75], v[54:55], off offset:1024 nt
	global_load_dwordx2 v[72:73], v[126:127], off offset:1024 nt
	global_load_dwordx2 v[70:71], v[128:129], off offset:1024 nt
	global_load_dwordx2 v[68:69], v[130:131], off offset:1024 nt
	global_load_dwordx2 v[66:67], v[4:5], off offset:1024 nt
	global_load_dwordx2 v[64:65], v[46:47], off offset:1536
	global_load_dwordx2 v[62:63], v[48:49], off offset:1536 nt
	global_load_dwordx2 v[60:61], v[50:51], off offset:1536 nt
	global_load_dwordx2 v[58:59], v[52:53], off offset:1536 nt
	global_load_dwordx2 v[56:57], v[54:55], off offset:1536 nt
	s_nop 0
	global_load_dwordx2 v[54:55], v[126:127], off offset:1536 nt
	global_load_dwordx2 v[52:53], v[128:129], off offset:1536 nt
	global_load_dwordx2 v[50:51], v[130:131], off offset:1536 nt
	global_load_dwordx2 v[48:49], v[4:5], off offset:1536 nt
	s_waitcnt vmcnt(35)
	v_lshlrev_b32_e32 v125, 16, v2
	v_and_b32_e32 v130, 0xffff0000, v2
	v_lshlrev_b32_e32 v131, 16, v3
	v_and_b32_e32 v132, 0xffff0000, v3
	v_mov_b32_e32 v2, v134
	v_mov_b32_e32 v3, v135
	v_mov_b32_e32 v4, v136
	v_mov_b32_e32 v5, v137
	v_mov_b32_e32 v126, v138
	v_mov_b32_e32 v127, v139
	v_mov_b32_e32 v128, v140
	v_mov_b32_e32 v129, v141
	s_waitcnt vmcnt(0)
	v_pk_add_f32 v[126:127], v[126:127], 1.0 op_sel_hi:[1,0]
	s_nop 0
	v_pk_mul_f32 v[2:3], v[2:3], v[126:127]
	v_pk_add_f32 v[128:129], v[128:129], 1.0 op_sel_hi:[1,0]
	v_div_scale_f32 v126, s[0:1], v2, v2, v125
	v_rcp_f32_e32 v127, v126
	v_pk_mul_f32 v[4:5], v[4:5], v[128:129]
	v_fma_f32 v128, -v126, v127, 1.0
	v_fmac_f32_e32 v127, v128, v127
	v_div_scale_f32 v128, vcc, v125, v2, v125
	v_mul_f32_e32 v129, v128, v127
	v_fma_f32 v133, -v126, v129, v128
	v_fmac_f32_e32 v129, v133, v127
	v_fma_f32 v126, -v126, v129, v128
	v_div_fmas_f32 v126, v126, v127, v129
	v_div_fixup_f32 v126, v126, v2, v125
	v_div_scale_f32 v2, s[0:1], v3, v3, v130
	v_rcp_f32_e32 v125, v2
	s_nop 0
	v_fma_f32 v127, -v2, v125, 1.0
	v_fmac_f32_e32 v125, v127, v125
	v_div_scale_f32 v127, vcc, v130, v3, v130
	v_mul_f32_e32 v128, v127, v125
	v_fma_f32 v129, -v2, v128, v127
	v_fmac_f32_e32 v128, v129, v125
	v_fma_f32 v2, -v2, v128, v127
	v_div_fmas_f32 v2, v2, v125, v128
	v_div_fixup_f32 v127, v2, v3, v130
	v_div_scale_f32 v2, s[0:1], v4, v4, v131
	v_rcp_f32_e32 v3, v2
	s_nop 0
	v_fma_f32 v125, -v2, v3, 1.0
	v_fmac_f32_e32 v3, v125, v3
	v_div_scale_f32 v125, vcc, v131, v4, v131
	v_mul_f32_e32 v128, v125, v3
	v_fma_f32 v129, -v2, v128, v125
	v_fmac_f32_e32 v128, v129, v3
	v_fma_f32 v2, -v2, v128, v125
	v_div_fmas_f32 v2, v2, v3, v128
	v_div_fixup_f32 v128, v2, v4, v131
	v_div_scale_f32 v2, s[0:1], v5, v5, v132
	v_rcp_f32_e32 v3, v2
	s_nop 0
	v_fma_f32 v4, -v2, v3, 1.0
	v_fmac_f32_e32 v3, v4, v3
	v_div_scale_f32 v4, vcc, v132, v5, v132
	v_mul_f32_e32 v125, v4, v3
	v_fma_f32 v129, -v2, v125, v4
	v_fmac_f32_e32 v125, v129, v3
	v_fma_f32 v2, -v2, v125, v4
	v_div_fmas_f32 v2, v2, v3, v125
	v_div_fixup_f32 v129, v2, v5, v132
	v_lshlrev_b32_e32 v2, 16, v104
	v_and_b32_e32 v3, 0xffff0000, v104
	v_pk_add_f32 v[2:3], v[2:3], 0 op_sel_hi:[1,0]
	v_lshlrev_b32_e32 v4, 16, v106
	v_and_b32_e32 v5, 0xffff0000, v106
	v_pk_add_f32 v[2:3], v[2:3], v[4:5]
	v_lshlrev_b32_e32 v4, 16, v108
	v_and_b32_e32 v5, 0xffff0000, v108
	v_pk_add_f32 v[2:3], v[2:3], v[4:5]
	v_lshlrev_b32_e32 v4, 16, v110
	v_and_b32_e32 v5, 0xffff0000, v110
	v_pk_add_f32 v[2:3], v[2:3], v[4:5]
	v_lshlrev_b32_e32 v4, 16, v112
	v_and_b32_e32 v5, 0xffff0000, v112
	v_pk_add_f32 v[2:3], v[2:3], v[4:5]
	v_lshlrev_b32_e32 v4, 16, v114
	v_and_b32_e32 v5, 0xffff0000, v114
	v_pk_add_f32 v[2:3], v[2:3], v[4:5]
	v_lshlrev_b32_e32 v4, 16, v116
	v_and_b32_e32 v5, 0xffff0000, v116
	v_pk_add_f32 v[2:3], v[2:3], v[4:5]
	v_lshlrev_b32_e32 v4, 16, v118
	v_and_b32_e32 v5, 0xffff0000, v118
	v_pk_add_f32 v[130:131], v[2:3], v[4:5]
	v_lshlrev_b32_e32 v2, 16, v105
	v_and_b32_e32 v3, 0xffff0000, v105
	v_pk_add_f32 v[2:3], v[2:3], 0 op_sel_hi:[1,0]
	v_lshlrev_b32_e32 v4, 16, v107
	v_and_b32_e32 v5, 0xffff0000, v107
	v_pk_add_f32 v[2:3], v[2:3], v[4:5]
	v_lshlrev_b32_e32 v4, 16, v109
	v_and_b32_e32 v5, 0xffff0000, v109
	v_pk_add_f32 v[2:3], v[2:3], v[4:5]
	v_lshlrev_b32_e32 v4, 16, v111
	v_and_b32_e32 v5, 0xffff0000, v111
	v_pk_add_f32 v[2:3], v[2:3], v[4:5]
	v_lshlrev_b32_e32 v4, 16, v113
	v_and_b32_e32 v5, 0xffff0000, v113
	v_pk_add_f32 v[2:3], v[2:3], v[4:5]
	v_lshlrev_b32_e32 v4, 16, v115
	v_and_b32_e32 v5, 0xffff0000, v115
	v_pk_add_f32 v[2:3], v[2:3], v[4:5]
	v_lshlrev_b32_e32 v4, 16, v117
	v_and_b32_e32 v5, 0xffff0000, v117
	v_pk_add_f32 v[2:3], v[2:3], v[4:5]
	v_lshlrev_b32_e32 v4, 16, v119
	v_and_b32_e32 v5, 0xffff0000, v119
	v_pk_add_f32 v[104:105], v[2:3], v[4:5]
	v_mov_b32_e32 v2, v142
	v_mov_b32_e32 v3, v143
	v_mov_b32_e32 v4, v144
	v_mov_b32_e32 v5, v145
	v_lshlrev_b32_e32 v109, 16, v103
	v_and_b32_e32 v110, 0xffff0000, v103
	v_pk_fma_f32 v[104:105], v[104:105], v[4:5], v[128:129]
	v_pk_fma_f32 v[106:107], v[130:131], v[2:3], v[126:127]
	v_mul_f32_e32 v3, v105, v105
	v_mul_f32_e32 v2, v107, v107
	v_fmac_f32_e32 v2, v106, v106
	v_fmac_f32_e32 v3, v104, v104
	v_add_f32_e32 v108, v2, v3
	v_mov_b32_e32 v2, v146
	v_mov_b32_e32 v3, v147
	v_mov_b32_e32 v4, v148
	v_mov_b32_e32 v5, v149
	v_pk_mul_f32 v[104:105], v[4:5], v[104:105]
	v_pk_mul_f32 v[106:107], v[2:3], v[106:107]
	v_mov_b32_e32 v2, v150
	v_mov_b32_e32 v3, v151
	v_mov_b32_e32 v4, v152
	v_mov_b32_e32 v5, v153
	v_pk_add_f32 v[4:5], v[4:5], 1.0 op_sel_hi:[1,0]
	v_pk_add_f32 v[2:3], v[2:3], 1.0 op_sel_hi:[1,0]
	v_pk_mul_f32 v[4:5], v[4:5], v[104:105]
	v_pk_mul_f32 v[2:3], v[2:3], v[106:107]
	v_lshlrev_b32_e32 v106, 16, v102
	v_cvt_pk_bf16_f32 v2, v2, v3
	v_cvt_pk_bf16_f32 v3, v4, v5
	global_store_dwordx2 v[46:47], v[2:3], off
	v_and_b32_e32 v107, 0xffff0000, v102
	v_mov_b32_e32 v2, v154
	v_mov_b32_e32 v3, v155
	v_mov_b32_e32 v4, v156
	v_mov_b32_e32 v5, v157
	v_mov_b32_e32 v102, v158
	v_mov_b32_e32 v103, v159
	v_mov_b32_e32 v104, v160
	v_mov_b32_e32 v105, v161
	v_pk_add_f32 v[102:103], v[102:103], 1.0 op_sel_hi:[1,0]
	s_nop 0
	v_pk_mul_f32 v[2:3], v[2:3], v[102:103]
	v_pk_add_f32 v[104:105], v[104:105], 1.0 op_sel_hi:[1,0]
	v_div_scale_f32 v102, s[0:1], v2, v2, v106
	v_rcp_f32_e32 v103, v102
	v_pk_mul_f32 v[4:5], v[4:5], v[104:105]
	v_fma_f32 v104, -v102, v103, 1.0
	v_fmac_f32_e32 v103, v104, v103
	v_div_scale_f32 v104, vcc, v106, v2, v106
	v_mul_f32_e32 v105, v104, v103
	v_fma_f32 v111, -v102, v105, v104
	v_fmac_f32_e32 v105, v111, v103
	v_fma_f32 v102, -v102, v105, v104
	v_div_fmas_f32 v102, v102, v103, v105
	v_div_fixup_f32 v102, v102, v2, v106
	v_div_scale_f32 v2, s[0:1], v3, v3, v107
	v_rcp_f32_e32 v103, v2
	s_nop 0
	v_fma_f32 v104, -v2, v103, 1.0
	v_fmac_f32_e32 v103, v104, v103
	v_div_scale_f32 v104, vcc, v107, v3, v107
	v_mul_f32_e32 v105, v104, v103
	v_fma_f32 v106, -v2, v105, v104
	v_fmac_f32_e32 v105, v106, v103
	v_fma_f32 v2, -v2, v105, v104
	v_div_fmas_f32 v2, v2, v103, v105
	v_div_fixup_f32 v103, v2, v3, v107
	v_div_scale_f32 v2, s[0:1], v4, v4, v109
	v_rcp_f32_e32 v3, v2
	s_nop 0
	v_fma_f32 v104, -v2, v3, 1.0
	v_fmac_f32_e32 v3, v104, v3
	v_div_scale_f32 v104, vcc, v109, v4, v109
	v_mul_f32_e32 v105, v104, v3
	v_fma_f32 v106, -v2, v105, v104
	v_fmac_f32_e32 v105, v106, v3
	v_fma_f32 v2, -v2, v105, v104
	v_div_fmas_f32 v2, v2, v3, v105
	v_div_fixup_f32 v104, v2, v4, v109
	v_div_scale_f32 v2, s[0:1], v5, v5, v110
	v_rcp_f32_e32 v3, v2
	s_nop 0
	v_fma_f32 v4, -v2, v3, 1.0
	v_fmac_f32_e32 v3, v4, v3
	v_div_scale_f32 v4, vcc, v110, v5, v110
	v_mul_f32_e32 v105, v4, v3
	v_fma_f32 v106, -v2, v105, v4
	v_fmac_f32_e32 v105, v106, v3
	v_fma_f32 v2, -v2, v105, v4
	v_div_fmas_f32 v2, v2, v3, v105
	v_div_fixup_f32 v105, v2, v5, v110
	v_lshlrev_b32_e32 v2, 16, v100
	v_and_b32_e32 v3, 0xffff0000, v100
	v_pk_add_f32 v[2:3], v[2:3], 0 op_sel_hi:[1,0]
	v_lshlrev_b32_e32 v4, 16, v96
	v_and_b32_e32 v5, 0xffff0000, v96
	v_pk_add_f32 v[2:3], v[2:3], v[4:5]
	v_lshlrev_b32_e32 v4, 16, v94
	v_and_b32_e32 v5, 0xffff0000, v94
	v_pk_add_f32 v[2:3], v[2:3], v[4:5]
	v_lshlrev_b32_e32 v4, 16, v92
	v_and_b32_e32 v5, 0xffff0000, v92
	v_pk_add_f32 v[2:3], v[2:3], v[4:5]
	v_lshlrev_b32_e32 v4, 16, v90
	v_and_b32_e32 v5, 0xffff0000, v90
	v_pk_add_f32 v[2:3], v[2:3], v[4:5]
	v_lshlrev_b32_e32 v4, 16, v88
	v_and_b32_e32 v5, 0xffff0000, v88
	v_pk_add_f32 v[2:3], v[2:3], v[4:5]
	v_lshlrev_b32_e32 v4, 16, v86
	v_and_b32_e32 v5, 0xffff0000, v86
	v_pk_add_f32 v[2:3], v[2:3], v[4:5]
	v_lshlrev_b32_e32 v4, 16, v84
	v_and_b32_e32 v5, 0xffff0000, v84
	v_pk_add_f32 v[106:107], v[2:3], v[4:5]
	v_lshlrev_b32_e32 v2, 16, v101
	v_and_b32_e32 v3, 0xffff0000, v101
	v_pk_add_f32 v[2:3], v[2:3], 0 op_sel_hi:[1,0]
	v_lshlrev_b32_e32 v4, 16, v97
	v_and_b32_e32 v5, 0xffff0000, v97
	v_pk_add_f32 v[2:3], v[2:3], v[4:5]
	v_lshlrev_b32_e32 v4, 16, v95
	v_and_b32_e32 v5, 0xffff0000, v95
	v_pk_add_f32 v[2:3], v[2:3], v[4:5]
	v_lshlrev_b32_e32 v4, 16, v93
	v_and_b32_e32 v5, 0xffff0000, v93
	v_pk_add_f32 v[2:3], v[2:3], v[4:5]
	v_lshlrev_b32_e32 v4, 16, v91
	v_and_b32_e32 v5, 0xffff0000, v91
	v_pk_add_f32 v[2:3], v[2:3], v[4:5]
	v_lshlrev_b32_e32 v4, 16, v89
	v_and_b32_e32 v5, 0xffff0000, v89
	v_pk_add_f32 v[2:3], v[2:3], v[4:5]
	v_lshlrev_b32_e32 v4, 16, v87
	v_and_b32_e32 v5, 0xffff0000, v87
	v_pk_add_f32 v[2:3], v[2:3], v[4:5]
	v_lshlrev_b32_e32 v4, 16, v85
	v_and_b32_e32 v5, 0xffff0000, v85
	v_pk_add_f32 v[84:85], v[2:3], v[4:5]
	v_mov_b32_e32 v2, v162
	v_mov_b32_e32 v3, v163
	v_mov_b32_e32 v4, v164
	v_mov_b32_e32 v5, v165
	v_lshlrev_b32_e32 v89, 16, v83
	v_and_b32_e32 v90, 0xffff0000, v83
	v_pk_fma_f32 v[84:85], v[84:85], v[4:5], v[104:105]
	v_pk_fma_f32 v[86:87], v[106:107], v[2:3], v[102:103]
	v_mul_f32_e32 v3, v85, v85
	v_mul_f32_e32 v2, v87, v87
	v_fmac_f32_e32 v2, v86, v86
	v_fmac_f32_e32 v3, v84, v84
	v_add_f32_e32 v2, v2, v3
	v_add_f32_e32 v88, v108, v2
	v_mov_b32_e32 v2, v166
	v_mov_b32_e32 v3, v167
	v_mov_b32_e32 v4, v168
	v_mov_b32_e32 v5, v169
	v_pk_mul_f32 v[84:85], v[4:5], v[84:85]
	v_pk_mul_f32 v[86:87], v[2:3], v[86:87]
	v_mov_b32_e32 v2, v170
	v_mov_b32_e32 v3, v171
	v_mov_b32_e32 v4, v172
	v_mov_b32_e32 v5, v173
	v_pk_add_f32 v[4:5], v[4:5], 1.0 op_sel_hi:[1,0]
	v_pk_add_f32 v[2:3], v[2:3], 1.0 op_sel_hi:[1,0]
	v_pk_mul_f32 v[4:5], v[4:5], v[84:85]
	v_pk_mul_f32 v[2:3], v[2:3], v[86:87]
	v_lshlrev_b32_e32 v86, 16, v82
	v_cvt_pk_bf16_f32 v2, v2, v3
	v_cvt_pk_bf16_f32 v3, v4, v5
	global_store_dwordx2 v[46:47], v[2:3], off offset:512
	v_and_b32_e32 v87, 0xffff0000, v82
	v_mov_b32_e32 v2, v174
	v_mov_b32_e32 v3, v175
	v_mov_b32_e32 v4, v176
	v_mov_b32_e32 v5, v177
	v_mov_b32_e32 v82, v178
	v_mov_b32_e32 v83, v179
	v_mov_b32_e32 v84, v180
	v_mov_b32_e32 v85, v181
	v_pk_add_f32 v[82:83], v[82:83], 1.0 op_sel_hi:[1,0]
	s_nop 0
	v_pk_mul_f32 v[2:3], v[2:3], v[82:83]
	v_pk_add_f32 v[84:85], v[84:85], 1.0 op_sel_hi:[1,0]
	v_div_scale_f32 v82, s[0:1], v2, v2, v86
	v_rcp_f32_e32 v83, v82
	v_pk_mul_f32 v[4:5], v[4:5], v[84:85]
	v_fma_f32 v84, -v82, v83, 1.0
	v_fmac_f32_e32 v83, v84, v83
	v_div_scale_f32 v84, vcc, v86, v2, v86
	v_mul_f32_e32 v85, v84, v83
	v_fma_f32 v91, -v82, v85, v84
	v_fmac_f32_e32 v85, v91, v83
	v_fma_f32 v82, -v82, v85, v84
	v_div_fmas_f32 v82, v82, v83, v85
	v_div_fixup_f32 v82, v82, v2, v86
	v_div_scale_f32 v2, s[0:1], v3, v3, v87
	v_rcp_f32_e32 v83, v2
	s_nop 0
	v_fma_f32 v84, -v2, v83, 1.0
	v_fmac_f32_e32 v83, v84, v83
	v_div_scale_f32 v84, vcc, v87, v3, v87
	v_mul_f32_e32 v85, v84, v83
	v_fma_f32 v86, -v2, v85, v84
	v_fmac_f32_e32 v85, v86, v83
	v_fma_f32 v2, -v2, v85, v84
	v_div_fmas_f32 v2, v2, v83, v85
	v_div_fixup_f32 v83, v2, v3, v87
	v_div_scale_f32 v2, s[0:1], v4, v4, v89
	v_rcp_f32_e32 v3, v2
	s_nop 0
	v_fma_f32 v84, -v2, v3, 1.0
	v_fmac_f32_e32 v3, v84, v3
	v_div_scale_f32 v84, vcc, v89, v4, v89
	v_mul_f32_e32 v85, v84, v3
	v_fma_f32 v86, -v2, v85, v84
	v_fmac_f32_e32 v85, v86, v3
	v_fma_f32 v2, -v2, v85, v84
	v_div_fmas_f32 v2, v2, v3, v85
	v_div_fixup_f32 v84, v2, v4, v89
	v_div_scale_f32 v2, s[0:1], v5, v5, v90
	v_rcp_f32_e32 v3, v2
	s_nop 0
	v_fma_f32 v4, -v2, v3, 1.0
	v_fmac_f32_e32 v3, v4, v3
	v_div_scale_f32 v4, vcc, v90, v5, v90
	v_mul_f32_e32 v85, v4, v3
	v_fma_f32 v86, -v2, v85, v4
	v_fmac_f32_e32 v85, v86, v3
	v_fma_f32 v2, -v2, v85, v4
	v_div_fmas_f32 v2, v2, v3, v85
	v_div_fixup_f32 v85, v2, v5, v90
	v_lshlrev_b32_e32 v2, 16, v80
	v_and_b32_e32 v3, 0xffff0000, v80
	v_pk_add_f32 v[2:3], v[2:3], 0 op_sel_hi:[1,0]
	v_lshlrev_b32_e32 v4, 16, v78
	v_and_b32_e32 v5, 0xffff0000, v78
	v_pk_add_f32 v[2:3], v[2:3], v[4:5]
	v_lshlrev_b32_e32 v4, 16, v76
	v_and_b32_e32 v5, 0xffff0000, v76
	v_pk_add_f32 v[2:3], v[2:3], v[4:5]
	v_lshlrev_b32_e32 v4, 16, v74
	v_and_b32_e32 v5, 0xffff0000, v74
	v_pk_add_f32 v[2:3], v[2:3], v[4:5]
	v_lshlrev_b32_e32 v4, 16, v72
	v_and_b32_e32 v5, 0xffff0000, v72
	v_pk_add_f32 v[2:3], v[2:3], v[4:5]
	v_lshlrev_b32_e32 v4, 16, v70
	v_and_b32_e32 v5, 0xffff0000, v70
	v_pk_add_f32 v[2:3], v[2:3], v[4:5]
	v_lshlrev_b32_e32 v4, 16, v68
	v_and_b32_e32 v5, 0xffff0000, v68
	v_pk_add_f32 v[2:3], v[2:3], v[4:5]
	v_lshlrev_b32_e32 v4, 16, v66
	v_and_b32_e32 v5, 0xffff0000, v66
	v_pk_add_f32 v[86:87], v[2:3], v[4:5]
	v_lshlrev_b32_e32 v2, 16, v81
	v_and_b32_e32 v3, 0xffff0000, v81
	v_pk_add_f32 v[2:3], v[2:3], 0 op_sel_hi:[1,0]
	v_lshlrev_b32_e32 v4, 16, v79
	v_and_b32_e32 v5, 0xffff0000, v79
	v_pk_add_f32 v[2:3], v[2:3], v[4:5]
	v_lshlrev_b32_e32 v4, 16, v77
	v_and_b32_e32 v5, 0xffff0000, v77
	v_pk_add_f32 v[2:3], v[2:3], v[4:5]
	v_lshlrev_b32_e32 v4, 16, v75
	v_and_b32_e32 v5, 0xffff0000, v75
	v_pk_add_f32 v[2:3], v[2:3], v[4:5]
	v_lshlrev_b32_e32 v4, 16, v73
	v_and_b32_e32 v5, 0xffff0000, v73
	v_pk_add_f32 v[2:3], v[2:3], v[4:5]
	v_lshlrev_b32_e32 v4, 16, v71
	v_and_b32_e32 v5, 0xffff0000, v71
	v_pk_add_f32 v[2:3], v[2:3], v[4:5]
	v_lshlrev_b32_e32 v4, 16, v69
	v_and_b32_e32 v5, 0xffff0000, v69
	v_pk_add_f32 v[2:3], v[2:3], v[4:5]
	v_lshlrev_b32_e32 v4, 16, v67
	v_and_b32_e32 v5, 0xffff0000, v67
	v_pk_add_f32 v[66:67], v[2:3], v[4:5]
	v_mov_b32_e32 v2, v182
	v_mov_b32_e32 v3, v183
	v_mov_b32_e32 v4, v184
	v_mov_b32_e32 v5, v185
	v_lshlrev_b32_e32 v71, 16, v65
	v_and_b32_e32 v72, 0xffff0000, v65
	v_pk_fma_f32 v[66:67], v[66:67], v[4:5], v[84:85]
	v_pk_fma_f32 v[68:69], v[86:87], v[2:3], v[82:83]
	v_mul_f32_e32 v3, v67, v67
	v_mul_f32_e32 v2, v69, v69
	v_fmac_f32_e32 v2, v68, v68
	v_fmac_f32_e32 v3, v66, v66
	v_add_f32_e32 v2, v2, v3
	v_add_f32_e32 v70, v88, v2
	v_mov_b32_e32 v2, v186
	v_mov_b32_e32 v3, v187
	v_mov_b32_e32 v4, v188
	v_mov_b32_e32 v5, v189
	v_pk_mul_f32 v[66:67], v[4:5], v[66:67]
	v_pk_mul_f32 v[68:69], v[2:3], v[68:69]
	v_mov_b32_e32 v2, v190
	v_mov_b32_e32 v3, v191
	v_mov_b32_e32 v4, v192
	v_mov_b32_e32 v5, v193
	v_pk_add_f32 v[4:5], v[4:5], 1.0 op_sel_hi:[1,0]
	v_pk_add_f32 v[2:3], v[2:3], 1.0 op_sel_hi:[1,0]
	v_pk_mul_f32 v[4:5], v[4:5], v[66:67]
	v_pk_mul_f32 v[2:3], v[2:3], v[68:69]
	v_lshlrev_b32_e32 v68, 16, v64
	v_cvt_pk_bf16_f32 v2, v2, v3
	v_cvt_pk_bf16_f32 v3, v4, v5
	global_store_dwordx2 v[46:47], v[2:3], off offset:1024
	v_and_b32_e32 v69, 0xffff0000, v64
	v_mov_b32_e32 v2, v194
	v_mov_b32_e32 v3, v195
	v_mov_b32_e32 v4, v196
	v_mov_b32_e32 v5, v197
	v_mov_b32_e32 v64, v204
	v_mov_b32_e32 v65, v205
	v_mov_b32_e32 v66, v206
	v_mov_b32_e32 v67, v207
	v_pk_add_f32 v[64:65], v[64:65], 1.0 op_sel_hi:[1,0]
	s_nop 0
	v_pk_mul_f32 v[2:3], v[2:3], v[64:65]
	v_pk_add_f32 v[66:67], v[66:67], 1.0 op_sel_hi:[1,0]
	v_div_scale_f32 v64, s[0:1], v2, v2, v68
	v_rcp_f32_e32 v65, v64
	v_pk_mul_f32 v[4:5], v[4:5], v[66:67]
	v_fma_f32 v66, -v64, v65, 1.0
	v_fmac_f32_e32 v65, v66, v65
	v_div_scale_f32 v66, vcc, v68, v2, v68
	v_mul_f32_e32 v67, v66, v65
	v_fma_f32 v73, -v64, v67, v66
	v_fmac_f32_e32 v67, v73, v65
	v_fma_f32 v64, -v64, v67, v66
	v_div_fmas_f32 v64, v64, v65, v67
	v_div_fixup_f32 v64, v64, v2, v68
	v_div_scale_f32 v2, s[0:1], v3, v3, v69
	v_rcp_f32_e32 v65, v2
	s_nop 0
	v_fma_f32 v66, -v2, v65, 1.0
	v_fmac_f32_e32 v65, v66, v65
	v_div_scale_f32 v66, vcc, v69, v3, v69
	v_mul_f32_e32 v67, v66, v65
	v_fma_f32 v68, -v2, v67, v66
	v_fmac_f32_e32 v67, v68, v65
	v_fma_f32 v2, -v2, v67, v66
	v_div_fmas_f32 v2, v2, v65, v67
	v_div_fixup_f32 v65, v2, v3, v69
	v_div_scale_f32 v2, s[0:1], v4, v4, v71
	v_rcp_f32_e32 v3, v2
	s_nop 0
	v_fma_f32 v66, -v2, v3, 1.0
	v_fmac_f32_e32 v3, v66, v3
	v_div_scale_f32 v66, vcc, v71, v4, v71
	v_mul_f32_e32 v67, v66, v3
	v_fma_f32 v68, -v2, v67, v66
	v_fmac_f32_e32 v67, v68, v3
	v_fma_f32 v2, -v2, v67, v66
	v_div_fmas_f32 v2, v2, v3, v67
	v_div_fixup_f32 v66, v2, v4, v71
	v_div_scale_f32 v2, s[0:1], v5, v5, v72
	v_rcp_f32_e32 v3, v2
	s_nop 0
	v_fma_f32 v4, -v2, v3, 1.0
	v_fmac_f32_e32 v3, v4, v3
	v_div_scale_f32 v4, vcc, v72, v5, v72
	v_mul_f32_e32 v67, v4, v3
	v_fma_f32 v68, -v2, v67, v4
	v_fmac_f32_e32 v67, v68, v3
	v_fma_f32 v2, -v2, v67, v4
	v_div_fmas_f32 v2, v2, v3, v67
	v_div_fixup_f32 v67, v2, v5, v72
	v_lshlrev_b32_e32 v2, 16, v62
	v_and_b32_e32 v3, 0xffff0000, v62
	v_pk_add_f32 v[2:3], v[2:3], 0 op_sel_hi:[1,0]
	v_lshlrev_b32_e32 v4, 16, v60
	v_and_b32_e32 v5, 0xffff0000, v60
	v_pk_add_f32 v[2:3], v[2:3], v[4:5]
	v_lshlrev_b32_e32 v4, 16, v58
	v_and_b32_e32 v5, 0xffff0000, v58
	v_pk_add_f32 v[2:3], v[2:3], v[4:5]
	v_lshlrev_b32_e32 v4, 16, v56
	v_and_b32_e32 v5, 0xffff0000, v56
	v_pk_add_f32 v[2:3], v[2:3], v[4:5]
	v_lshlrev_b32_e32 v4, 16, v54
	v_and_b32_e32 v5, 0xffff0000, v54
	v_pk_add_f32 v[2:3], v[2:3], v[4:5]
	v_lshlrev_b32_e32 v4, 16, v52
	v_and_b32_e32 v5, 0xffff0000, v52
	v_pk_add_f32 v[2:3], v[2:3], v[4:5]
	v_lshlrev_b32_e32 v4, 16, v50
	v_and_b32_e32 v5, 0xffff0000, v50
	v_pk_add_f32 v[2:3], v[2:3], v[4:5]
	v_lshlrev_b32_e32 v4, 16, v48
	v_and_b32_e32 v5, 0xffff0000, v48
	v_pk_add_f32 v[68:69], v[2:3], v[4:5]
	v_lshlrev_b32_e32 v2, 16, v63
	v_and_b32_e32 v3, 0xffff0000, v63
	v_pk_add_f32 v[2:3], v[2:3], 0 op_sel_hi:[1,0]
	v_lshlrev_b32_e32 v4, 16, v61
	v_and_b32_e32 v5, 0xffff0000, v61
	v_pk_add_f32 v[2:3], v[2:3], v[4:5]
	v_lshlrev_b32_e32 v4, 16, v59
	v_and_b32_e32 v5, 0xffff0000, v59
	v_pk_add_f32 v[2:3], v[2:3], v[4:5]
	v_lshlrev_b32_e32 v4, 16, v57
	v_and_b32_e32 v5, 0xffff0000, v57
	v_pk_add_f32 v[2:3], v[2:3], v[4:5]
	v_lshlrev_b32_e32 v4, 16, v55
	v_and_b32_e32 v5, 0xffff0000, v55
	v_pk_add_f32 v[2:3], v[2:3], v[4:5]
	v_lshlrev_b32_e32 v4, 16, v53
	v_and_b32_e32 v5, 0xffff0000, v53
	v_pk_add_f32 v[2:3], v[2:3], v[4:5]
	v_lshlrev_b32_e32 v4, 16, v51
	v_and_b32_e32 v5, 0xffff0000, v51
	v_pk_add_f32 v[2:3], v[2:3], v[4:5]
	v_lshlrev_b32_e32 v4, 16, v49
	v_and_b32_e32 v5, 0xffff0000, v49
	v_pk_add_f32 v[48:49], v[2:3], v[4:5]
	v_mov_b32_e32 v2, v208
	v_mov_b32_e32 v3, v209
	v_mov_b32_e32 v4, v210
	v_mov_b32_e32 v5, v211
	v_mov_b32_e32 v50, v214
	v_mov_b32_e32 v51, v215
	v_mov_b32_e32 v52, v216
	v_mov_b32_e32 v53, v217
	v_pk_fma_f32 v[4:5], v[48:49], v[4:5], v[66:67]
	v_pk_fma_f32 v[54:55], v[68:69], v[2:3], v[64:65]
	v_mul_f32_e32 v3, v5, v5
	v_mul_f32_e32 v2, v55, v55
	v_fmac_f32_e32 v2, v54, v54
	v_fmac_f32_e32 v3, v4, v4
	v_add_f32_e32 v2, v2, v3
	v_add_f32_e32 v48, v70, v2
	v_pk_mul_f32 v[2:3], v[52:53], v[4:5]
	v_pk_mul_f32 v[4:5], v[50:51], v[54:55]
	v_mov_b32_e32 v50, v218
	v_mov_b32_e32 v51, v219
	v_mov_b32_e32 v52, v220
	v_mov_b32_e32 v53, v221
	v_pk_add_f32 v[52:53], v[52:53], 1.0 op_sel_hi:[1,0]
	v_pk_add_f32 v[50:51], v[50:51], 1.0 op_sel_hi:[1,0]
	v_pk_mul_f32 v[2:3], v[52:53], v[2:3]
	v_pk_mul_f32 v[4:5], v[50:51], v[4:5]
	s_nop 0
	v_cvt_pk_bf16_f32 v4, v4, v5
	v_cvt_pk_bf16_f32 v5, v2, v3
	v_mov_b32_dpp v2, v48 quad_perm:[1,0,3,2] row_mask:0xf bank_mask:0xf
	global_store_dwordx2 v[46:47], v[4:5], off offset:1536
	s_waitcnt lgkmcnt(0)
	v_add_f32_e32 v2, v48, v2
	s_nop 1
	v_mov_b32_dpp v3, v2 quad_perm:[2,3,0,1] row_mask:0xf bank_mask:0xf
	s_waitcnt lgkmcnt(0)
	v_add_f32_e32 v2, v2, v3
	s_nop 1
	v_mov_b32_dpp v3, v2 row_half_mirror row_mask:0xf bank_mask:0xf
	s_waitcnt lgkmcnt(0)
	v_add_f32_e32 v2, v2, v3
	s_nop 1
	v_mov_b32_dpp v3, v2 row_mirror row_mask:0xf bank_mask:0xf
	s_waitcnt lgkmcnt(0)
	v_add_f32_e32 v2, v2, v3
	v_mov_b32_e32 v3, v2
	s_nop 1
	v_permlane16_swap_b32_e32 v2, v3
	s_waitcnt lgkmcnt(0)
	v_add_f32_e32 v2, v2, v3
	v_mov_b32_e32 v3, v2
	s_nop 1
	v_permlane32_swap_b32_e32 v2, v3
	s_and_saveexec_b64 s[0:1], s[36:37]
	s_cbranch_execz .LBB0_1637
	s_waitcnt lgkmcnt(0)
	v_add_f32_e32 v2, v2, v3
	v_lshl_add_u64 v[4:5], s[86:87], 0, v[44:45]
	v_cndmask_b32_e64 v2, 0, v2, s[38:39]
	global_store_dword v[4:5], v2, off
	s_branch .LBB0_1637
